# v5b + GEMM loops: 8 of 16 LDS-DMA loads per iteration use the saddr form (no 64-bit VALU address add), measure 1
# speedup vs baseline: 1.0096x; 1.0096x over previous
; #define PG8_STAGE(bufoff, gbase, voff) do { _Pragma("unroll") for (int _i = 0; _i < 2; ++_i) \
;         __builtin_amdgcn_global_load_lds((const unsigned*)((const char*)(gbase) + (voff)[_i]), (LAS unsigned*)(lds + (bufoff) + ldsw + _i * 8192), 16, 0, 0); } while (0)
; #define PG8_LDA(dst, b, h) do { _Pragma("unroll") for (int m = 0; m < 4; ++m) _Pragma("unroll") for (int k = 0; k < 2; ++k) dst[m][k] = *(const LAS bf16x8*)(lds + PG8_SA(b, h) + aoff + m * 2048 + k * 1024); } while (0)
; #define PG8_LDB(dst, b, h) do { _Pragma("unroll") for (int n = 0; n < 2; ++n) _Pragma("unroll") for (int k = 0; k < 2; ++k) dst[n][k] = *(const LAS bf16x8*)(lds + PG8_SB(b, h) + boff + n * 2048 + k * 1024); } while (0)
; #define PG8_MMA(ai, bj, At, Bt) do { __builtin_amdgcn_s_setprio(1); _Pragma("unroll") for (int m = 0; m < 4; ++m) _Pragma("unroll") for (int n = 0; n < 2; ++n) _Pragma("unroll") for (int k = 0; k < 2; ++k) \
;         acc[ai][bj][m][n] = __builtin_amdgcn_mfma_f32_16x16x32_bf16(Bt[n][k], At[m][k], acc[ai][bj][m][n], 0, 0, 0); __builtin_amdgcn_s_setprio(0); } while (0)
; #define PG8_WAIT_V(n) asm volatile("s_waitcnt vmcnt(" #n ")" ::: "memory")
; #define PG8_WAIT_L(n) asm volatile("s_waitcnt lgkmcnt(" #n ")" ::: "memory")
; #define PG8_BAR __builtin_amdgcn_s_barrier()
; template <class Epi, class Ptrs>
; __device__ __forceinline__ void gemm_phase(LAS unsigned char* lds, const int K, const StaticOrder& S, const Ptrs& P, const Epi& E) {
;     ...
;             const char* a2 = last ? nA : cA + (size_t)(t + 2) * kstep; const char* b2 = last ? nB : cB + (size_t)(t + 2) * kstep;
;             const char* a3 = a2 + kstep; const char* b3 = b2 + kstep;
;             PG8_LDB(B0, 0, 0); PG8_SCHED; PG8_LDA(At, 0, 0); PG8_STAGE(PG8_SA(1, 1), a1 + hstep, voffA);
;             PG8_WAIT_L(8); PG8_BAR; PG8_WAIT_L(0); PG8_MMA(0, 0, At, B0); PG8_BAR; PG8_SCHED;
;             PG8_LDB(B1, 0, 1); PG8_STAGE(PG8_SB(0, 0), b2, voffB);
;             PG8_BAR; PG8_WAIT_L(0); PG8_MMA(0, 1, At, B1); PG8_BAR;
;             PG8_LDA(At, 0, 1); PG8_STAGE(PG8_SA(0, 0), a2, voffA);
;             PG8_BAR; PG8_WAIT_L(0); PG8_MMA(1, 0, At, B0); PG8_BAR; PG8_SCHED;
;             PG8_STAGE(PG8_SB(0, 1), b2 + hstep, voffB);
;             PG8_WAIT_V(6); PG8_BAR; PG8_MMA(1, 1, At, B1); PG8_BAR;
;             PG8_LDB(B0, 1, 0); PG8_SCHED; PG8_LDA(At, 1, 0); PG8_STAGE(PG8_SA(0, 1), a2 + hstep, voffA);
.LBB0_127:
	ds_read_b128 v[150:153], v205
	ds_read_b128 v[154:157], v205 offset:1024
	ds_read_b128 v[158:161], v205 offset:2048
	ds_read_b128 v[162:165], v205 offset:3072
	s_add_u32 s69, s6, 0xfffc0080
	s_addc_u32 s71, s7, -1
	s_cmp_eq_u32 s63, 12
	s_cselect_b32 s81, s1, s71
	s_cselect_b32 s80, s0, s69
	s_cselect_b32 s79, s73, s25
	s_cselect_b32 s78, s72, s20
	s_add_i32 m0, s67, 0xc000
	ds_read_b128 v[166:169], v206
	ds_read_b128 v[170:173], v206 offset:1024
	ds_read_b128 v[174:177], v206 offset:2048
	ds_read_b128 v[178:181], v206 offset:3072
	ds_read_b128 v[182:185], v206 offset:4096
	ds_read_b128 v[186:189], v206 offset:5120
	ds_read_b128 v[190:193], v206 offset:6144
	ds_read_b128 v[194:197], v206 offset:7168
	global_load_lds_dwordx4 v142, s[6:7]
	s_add_i32 m0, s67, 0xe000
	s_nop 0
	global_load_lds_dwordx4 v144, s[6:7]
	s_waitcnt lgkmcnt(8)
	s_barrier
	s_waitcnt lgkmcnt(0)
	s_setprio 1
	s_waitcnt lgkmcnt(0)
	v_mfma_f32_16x16x32_bf16 v[120:123], v[150:153], v[166:169], v[120:123]
	v_mfma_f32_16x16x32_bf16 v[120:123], v[154:157], v[170:173], v[120:123]
	v_mfma_f32_16x16x32_bf16 v[116:119], v[162:165], v[170:173], v[116:119]
	v_mfma_f32_16x16x32_bf16 v[116:119], v[158:161], v[166:169], v[116:119]
	v_mfma_f32_16x16x32_bf16 v[100:103], v[158:161], v[174:177], v[100:103]
	v_mfma_f32_16x16x32_bf16 v[100:103], v[162:165], v[178:181], v[100:103]
	v_mfma_f32_16x16x32_bf16 v[104:107], v[154:157], v[178:181], v[104:107]
	v_mfma_f32_16x16x32_bf16 v[104:107], v[150:153], v[174:177], v[104:107]
	v_mfma_f32_16x16x32_bf16 v[88:91], v[150:153], v[182:185], v[88:91]
	v_mfma_f32_16x16x32_bf16 v[88:91], v[154:157], v[186:189], v[88:91]
	v_mfma_f32_16x16x32_bf16 v[84:87], v[162:165], v[186:189], v[84:87]
	v_mfma_f32_16x16x32_bf16 v[84:87], v[158:161], v[182:185], v[84:87]
	v_mfma_f32_16x16x32_bf16 v[68:71], v[158:161], v[190:193], v[68:71]
	v_mfma_f32_16x16x32_bf16 v[68:71], v[162:165], v[194:197], v[68:71]
	v_mfma_f32_16x16x32_bf16 v[72:75], v[154:157], v[194:197], v[72:75]
	v_mfma_f32_16x16x32_bf16 v[72:75], v[150:153], v[190:193], v[72:75]
	s_setprio 0
	s_barrier
	s_add_i32 s69, s91, s65
	v_lshl_add_u64 v[202:203], s[78:79], 0, v[134:135]
	s_mov_b32 m0, s69
	ds_read_b128 v[198:201], v207
	ds_read_b128 v[210:213], v207 offset:1024
	ds_read_b128 v[214:217], v207 offset:2048
	ds_read_b128 v[218:221], v207 offset:3072
	global_load_lds_dwordx4 v[202:203], off
	v_lshl_add_u64 v[222:223], s[78:79], 0, v[138:139]
	s_add_i32 m0, s69, 0x2000
	s_nop 0
	global_load_lds_dwordx4 v[222:223], off
	s_barrier
	s_waitcnt lgkmcnt(0)
	s_setprio 1
	s_waitcnt lgkmcnt(0)
	v_mfma_f32_16x16x32_bf16 v[124:127], v[198:201], v[166:169], v[124:127]
	v_mfma_f32_16x16x32_bf16 v[124:127], v[210:213], v[170:173], v[124:127]
	v_mfma_f32_16x16x32_bf16 v[112:115], v[218:221], v[170:173], v[112:115]
	v_mfma_f32_16x16x32_bf16 v[112:115], v[214:217], v[166:169], v[112:115]
	v_mfma_f32_16x16x32_bf16 v[96:99], v[214:217], v[174:177], v[96:99]
	v_mfma_f32_16x16x32_bf16 v[96:99], v[218:221], v[178:181], v[96:99]
	v_mfma_f32_16x16x32_bf16 v[108:111], v[210:213], v[178:181], v[108:111]
	v_mfma_f32_16x16x32_bf16 v[108:111], v[198:201], v[174:177], v[108:111]
	v_mfma_f32_16x16x32_bf16 v[92:95], v[198:201], v[182:185], v[92:95]
	v_mfma_f32_16x16x32_bf16 v[92:95], v[210:213], v[186:189], v[92:95]
	v_mfma_f32_16x16x32_bf16 v[80:83], v[218:221], v[186:189], v[80:83]
	v_mfma_f32_16x16x32_bf16 v[80:83], v[214:217], v[182:185], v[80:83]
	v_mfma_f32_16x16x32_bf16 v[64:67], v[214:217], v[190:193], v[64:67]
	v_mfma_f32_16x16x32_bf16 v[64:67], v[218:221], v[194:197], v[64:67]
	v_mfma_f32_16x16x32_bf16 v[76:79], v[210:213], v[194:197], v[76:79]
	v_mfma_f32_16x16x32_bf16 v[76:79], v[198:201], v[190:193], v[76:79]
	s_setprio 0
	s_mov_b32 m0, s67
	v_lshl_add_u64 v[224:225], s[80:81], 0, v[132:133]
	s_barrier
	ds_read_b128 v[166:169], v206 offset:16384
	ds_read_b128 v[170:173], v206 offset:17408
	ds_read_b128 v[174:177], v206 offset:18432
	ds_read_b128 v[178:181], v206 offset:19456
	ds_read_b128 v[182:185], v206 offset:20480
	ds_read_b128 v[186:189], v206 offset:21504
	ds_read_b128 v[190:193], v206 offset:22528
	ds_read_b128 v[194:197], v206 offset:23552
	global_load_lds_dwordx4 v[224:225], off
	v_lshl_add_u64 v[226:227], s[80:81], 0, v[136:137]
	s_mov_b32 m0, s75
	s_nop 0
	global_load_lds_dwordx4 v[226:227], off
	s_barrier
	s_waitcnt lgkmcnt(0)
	s_setprio 1
	s_waitcnt lgkmcnt(0)
	v_mfma_f32_16x16x32_bf16 v[56:59], v[150:153], v[166:169], v[56:59]
	v_mfma_f32_16x16x32_bf16 v[56:59], v[154:157], v[170:173], v[56:59]
	v_mfma_f32_16x16x32_bf16 v[52:55], v[162:165], v[170:173], v[52:55]
	v_mfma_f32_16x16x32_bf16 v[52:55], v[158:161], v[166:169], v[52:55]
	v_mfma_f32_16x16x32_bf16 v[36:39], v[158:161], v[174:177], v[36:39]
	v_mfma_f32_16x16x32_bf16 v[36:39], v[162:165], v[178:181], v[36:39]
	v_mfma_f32_16x16x32_bf16 v[40:43], v[154:157], v[178:181], v[40:43]
	v_mfma_f32_16x16x32_bf16 v[40:43], v[150:153], v[174:177], v[40:43]
	v_mfma_f32_16x16x32_bf16 v[24:27], v[150:153], v[182:185], v[24:27]
	v_mfma_f32_16x16x32_bf16 v[24:27], v[154:157], v[186:189], v[24:27]
	v_mfma_f32_16x16x32_bf16 v[20:23], v[162:165], v[186:189], v[20:23]
	v_mfma_f32_16x16x32_bf16 v[20:23], v[158:161], v[182:185], v[20:23]
	v_mfma_f32_16x16x32_bf16 v[4:7], v[158:161], v[190:193], v[4:7]
	v_mfma_f32_16x16x32_bf16 v[4:7], v[162:165], v[194:197], v[4:7]
	v_mfma_f32_16x16x32_bf16 v[8:11], v[154:157], v[194:197], v[8:11]
	v_mfma_f32_16x16x32_bf16 v[8:11], v[150:153], v[190:193], v[8:11]
	s_setprio 0
	s_barrier
	s_add_u32 s82, s78, 0x40000
	s_addc_u32 s83, s79, 0
	s_add_i32 s69, s92, s65
	s_mov_b32 m0, s69
	s_nop 0
	global_load_lds_dwordx4 v134, s[82:83]
	s_add_i32 m0, s69, 0x2000
	s_nop 0
	global_load_lds_dwordx4 v138, s[82:83]
	s_waitcnt vmcnt(6)
	s_barrier
; #define PG8_STAGE(bufoff, gbase, voff) do { _Pragma("unroll") for (int _i = 0; _i < 2; ++_i) \
;         __builtin_amdgcn_global_load_lds((const unsigned*)((const char*)(gbase) + (voff)[_i]), (LAS unsigned*)(lds + (bufoff) + ldsw + _i * 8192), 16, 0, 0); } while (0)
; #define PG8_LDA(dst, b, h) do { _Pragma("unroll") for (int m = 0; m < 4; ++m) _Pragma("unroll") for (int k = 0; k < 2; ++k) dst[m][k] = *(const LAS bf16x8*)(lds + PG8_SA(b, h) + aoff + m * 2048 + k * 1024); } while (0)
; #define PG8_LDB(dst, b, h) do { _Pragma("unroll") for (int n = 0; n < 2; ++n) _Pragma("unroll") for (int k = 0; k < 2; ++k) dst[n][k] = *(const LAS bf16x8*)(lds + PG8_SB(b, h) + boff + n * 2048 + k * 1024); } while (0)
; #define PG8_MMA(ai, bj, At, Bt) do { __builtin_amdgcn_s_setprio(1); _Pragma("unroll") for (int m = 0; m < 4; ++m) _Pragma("unroll") for (int n = 0; n < 2; ++n) _Pragma("unroll") for (int k = 0; k < 2; ++k) \
;         acc[ai][bj][m][n] = __builtin_amdgcn_mfma_f32_16x16x32_bf16(Bt[n][k], At[m][k], acc[ai][bj][m][n], 0, 0, 0); __builtin_amdgcn_s_setprio(0); } while (0)
; #define PG8_WAIT_V(n) asm volatile("s_waitcnt vmcnt(" #n ")" ::: "memory")
; #define PG8_WAIT_L(n) asm volatile("s_waitcnt lgkmcnt(" #n ")" ::: "memory")
; #define PG8_BAR __builtin_amdgcn_s_barrier()
; #define PG8_SCHED __builtin_amdgcn_sched_barrier(0)
; template <class Epi, class Ptrs>
; __device__ __forceinline__ void gemm_phase(LAS unsigned char* lds, const int K, const StaticOrder& S, const Ptrs& P, const Epi& E) {
;     ...
;             PG8_WAIT_V(6); PG8_BAR; PG8_MMA(1, 1, At, B1); PG8_BAR;
;             PG8_LDB(B0, 1, 0); PG8_SCHED; PG8_LDA(At, 1, 0); PG8_STAGE(PG8_SA(0, 1), a2 + hstep, voffA);
;             PG8_WAIT_L(8); PG8_BAR; PG8_WAIT_L(0); PG8_MMA(0, 0, At, B0); PG8_BAR; PG8_SCHED;
;             PG8_LDB(B1, 1, 1); PG8_STAGE(PG8_SB(1, 0), b3, voffB);
;             PG8_BAR; PG8_WAIT_L(0); PG8_MMA(0, 1, At, B1); PG8_BAR;
;             PG8_LDA(At, 1, 1); PG8_STAGE(PG8_SA(1, 0), a3, voffA);
;             PG8_BAR; PG8_WAIT_L(0); PG8_MMA(1, 0, At, B0); PG8_BAR; PG8_SCHED;
	s_setprio 1
	v_mfma_f32_16x16x32_bf16 v[60:63], v[198:201], v[166:169], v[60:63]
	v_mfma_f32_16x16x32_bf16 v[60:63], v[210:213], v[170:173], v[60:63]
	v_mfma_f32_16x16x32_bf16 v[48:51], v[218:221], v[170:173], v[48:51]
	v_mfma_f32_16x16x32_bf16 v[48:51], v[214:217], v[166:169], v[48:51]
	v_mfma_f32_16x16x32_bf16 v[32:35], v[214:217], v[174:177], v[32:35]
	v_mfma_f32_16x16x32_bf16 v[32:35], v[218:221], v[178:181], v[32:35]
	v_mfma_f32_16x16x32_bf16 v[44:47], v[210:213], v[178:181], v[44:47]
	v_mfma_f32_16x16x32_bf16 v[44:47], v[198:201], v[174:177], v[44:47]
	v_mfma_f32_16x16x32_bf16 v[28:31], v[198:201], v[182:185], v[28:31]
	v_mfma_f32_16x16x32_bf16 v[28:31], v[210:213], v[186:189], v[28:31]
	v_mfma_f32_16x16x32_bf16 v[16:19], v[218:221], v[186:189], v[16:19]
	v_mfma_f32_16x16x32_bf16 v[16:19], v[214:217], v[182:185], v[16:19]
	v_mfma_f32_16x16x32_bf16 v[0:3], v[214:217], v[190:193], v[0:3]
	v_mfma_f32_16x16x32_bf16 v[0:3], v[218:221], v[194:197], v[0:3]
	v_mfma_f32_16x16x32_bf16 v[12:15], v[210:213], v[194:197], v[12:15]
	v_mfma_f32_16x16x32_bf16 v[12:15], v[198:201], v[190:193], v[12:15]
	s_setprio 0
	s_add_i32 s69, 0, 0x18000
	v_add_u32_e32 v140, s69, v131
	s_barrier
	ds_read_b128 v[150:153], v140
	ds_read_b128 v[154:157], v140 offset:1024
	ds_read_b128 v[158:161], v140 offset:2048
	ds_read_b128 v[162:165], v140 offset:3072
	s_add_u32 s80, s80, 0x40000
	s_addc_u32 s81, s81, 0
	s_mov_b32 m0, s77
	ds_read_b128 v[166:169], v206 offset:32768
	ds_read_b128 v[170:173], v206 offset:33792
	ds_read_b128 v[174:177], v206 offset:34816
	ds_read_b128 v[178:181], v206 offset:35840
	ds_read_b128 v[182:185], v206 offset:36864
	ds_read_b128 v[186:189], v206 offset:37888
	ds_read_b128 v[190:193], v206 offset:38912
	ds_read_b128 v[194:197], v206 offset:39936
	global_load_lds_dwordx4 v132, s[80:81]
	s_mov_b32 m0, s85
	s_nop 0
	global_load_lds_dwordx4 v136, s[80:81]
	s_waitcnt lgkmcnt(8)
	s_barrier
	s_waitcnt lgkmcnt(0)
	s_setprio 1
	s_waitcnt lgkmcnt(0)
	v_mfma_f32_16x16x32_bf16 v[120:123], v[150:153], v[166:169], v[120:123]
	v_mfma_f32_16x16x32_bf16 v[120:123], v[154:157], v[170:173], v[120:123]
	v_mfma_f32_16x16x32_bf16 v[116:119], v[162:165], v[170:173], v[116:119]
	v_mfma_f32_16x16x32_bf16 v[116:119], v[158:161], v[166:169], v[116:119]
	v_mfma_f32_16x16x32_bf16 v[100:103], v[158:161], v[174:177], v[100:103]
	v_mfma_f32_16x16x32_bf16 v[100:103], v[162:165], v[178:181], v[100:103]
	v_mfma_f32_16x16x32_bf16 v[104:107], v[154:157], v[178:181], v[104:107]
	v_mfma_f32_16x16x32_bf16 v[104:107], v[150:153], v[174:177], v[104:107]
	v_mfma_f32_16x16x32_bf16 v[88:91], v[150:153], v[182:185], v[88:91]
	v_mfma_f32_16x16x32_bf16 v[88:91], v[154:157], v[186:189], v[88:91]
	v_mfma_f32_16x16x32_bf16 v[84:87], v[162:165], v[186:189], v[84:87]
	v_mfma_f32_16x16x32_bf16 v[84:87], v[158:161], v[182:185], v[84:87]
	v_mfma_f32_16x16x32_bf16 v[68:71], v[158:161], v[190:193], v[68:71]
	v_mfma_f32_16x16x32_bf16 v[68:71], v[162:165], v[194:197], v[68:71]
	v_mfma_f32_16x16x32_bf16 v[72:75], v[154:157], v[194:197], v[72:75]
	v_mfma_f32_16x16x32_bf16 v[72:75], v[150:153], v[190:193], v[72:75]
	s_setprio 0
	s_barrier
	s_add_i32 s71, 0, 0x1c000
	s_add_i32 s69, s69, s65
	v_add_u32_e32 v140, s71, v131
	v_lshl_add_u64 v[202:203], v[202:203], 0, s[58:59]
	s_mov_b32 m0, s69
	ds_read_b128 v[198:201], v140
	ds_read_b128 v[210:213], v140 offset:1024
	ds_read_b128 v[214:217], v140 offset:2048
	ds_read_b128 v[218:221], v140 offset:3072
	global_load_lds_dwordx4 v[202:203], off
	v_lshl_add_u64 v[202:203], v[222:223], 0, s[58:59]
	s_add_i32 m0, s69, 0x2000
	s_nop 0
	global_load_lds_dwordx4 v[202:203], off
	s_barrier
	s_waitcnt lgkmcnt(0)
	s_setprio 1
	s_waitcnt lgkmcnt(0)
	v_mfma_f32_16x16x32_bf16 v[124:127], v[198:201], v[166:169], v[124:127]
	v_mfma_f32_16x16x32_bf16 v[124:127], v[210:213], v[170:173], v[124:127]
	v_mfma_f32_16x16x32_bf16 v[112:115], v[218:221], v[170:173], v[112:115]
	v_mfma_f32_16x16x32_bf16 v[112:115], v[214:217], v[166:169], v[112:115]
	v_mfma_f32_16x16x32_bf16 v[96:99], v[214:217], v[174:177], v[96:99]
	v_mfma_f32_16x16x32_bf16 v[96:99], v[218:221], v[178:181], v[96:99]
	v_mfma_f32_16x16x32_bf16 v[108:111], v[210:213], v[178:181], v[108:111]
	v_mfma_f32_16x16x32_bf16 v[108:111], v[198:201], v[174:177], v[108:111]
	v_mfma_f32_16x16x32_bf16 v[92:95], v[198:201], v[182:185], v[92:95]
	v_mfma_f32_16x16x32_bf16 v[92:95], v[210:213], v[186:189], v[92:95]
	v_mfma_f32_16x16x32_bf16 v[80:83], v[218:221], v[186:189], v[80:83]
	v_mfma_f32_16x16x32_bf16 v[80:83], v[214:217], v[182:185], v[80:83]
	v_mfma_f32_16x16x32_bf16 v[64:67], v[214:217], v[190:193], v[64:67]
	v_mfma_f32_16x16x32_bf16 v[64:67], v[218:221], v[194:197], v[64:67]
	v_mfma_f32_16x16x32_bf16 v[76:79], v[210:213], v[194:197], v[76:79]
	v_mfma_f32_16x16x32_bf16 v[76:79], v[198:201], v[190:193], v[76:79]
	s_setprio 0
	s_mov_b32 m0, s89
	v_lshl_add_u64 v[202:203], v[224:225], 0, s[58:59]
	s_barrier
; #define PG8_WAIT_V(n) asm volatile("s_waitcnt vmcnt(" #n ")" ::: "memory")
; template <class Epi, class Ptrs>
; __device__ __forceinline__ void gemm_phase(LAS unsigned char* lds, const int K, const StaticOrder& S, const Ptrs& P, const Epi& E) {
;     ...
;             PG8_BAR; PG8_WAIT_L(0); PG8_MMA(1, 0, At, B0); PG8_BAR; PG8_SCHED;
;             PG8_STAGE(PG8_SB(1, 1), b3 + hstep, voffB);
;             PG8_WAIT_V(6); PG8_BAR; PG8_MMA(1, 1, At, B1); PG8_BAR;
;         }
;     __device__ __forceinline__ void operator()(const f32x4 (&acc)[2][2][4][2], const Unit& u, int ui, int wr, int wc, int fr, int fq) const {
;         const int pn = u.pn;
;         if (pn < 8) {
;             bf16_t* base = (bf16_t*)(ws + WS_U) + (size_t)(u.pm * 256 + wr * 64 + fr) * DM + pn * 128 + wc * 32 + 8 * fq;
; #pragma unroll
;             for (int ai = 0; ai < 2; ++ai)
; #pragma unroll
;                 for (int m = 0; m < 4; ++m) {
;                     const f32x4 g0 = g1_4(acc[ai][0][m][0], acc[ai][1][m][0]), g1 = g1_4(acc[ai][0][m][1], acc[ai][1][m][1]);
;                     *(u32x4*)(base + (size_t)(ai * 128 + m * 16) * DM) = pack8(g0, g1); }
;             return; }
;         if (pn >= 17 && pn < 21) {
;             bf16_t* base = (bf16_t*)(dout + DO_GVT) + (size_t)((pn - 17) * 256 + wr * 64 + fr) * MTOK + u.pm * 256 + wc * 32 + 8 * fq;
;             float* pp = (float*)(ws + WS_PART) + (size_t)(u.pm * 256 + wc * 32 + 8 * fq) * 8 + (pn - 17) * 2 + wr;
; #pragma unroll
;             for (int bj = 0; bj < 2; ++bj) { f32x4 sq0 = {0.f, 0.f, 0.f, 0.f}, sq1 = {0.f, 0.f, 0.f, 0.f};
; #pragma unroll
;                 for (int ai = 0; ai < 2; ++ai)
; #pragma unroll
;                     for (int m = 0; m < 4; ++m) { const f32x4 g0 = gelu4(acc[ai][bj][m][0]), g1 = gelu4(acc[ai][bj][m][1]);
;                         sq0 += g0 * g0; sq1 += g1 * g1;
;                         *(u32x4*)(base + (size_t)(ai * 128 + m * 16) * MTOK + bj * 128) = pack8(g0, g1); }
; #pragma unroll
;                 for (int j = 0; j < 4; ++j) { const float t0 = row16_sum(sq0[j]), t1 = row16_sum(sq1[j]); if (fr == 0) { pp[(size_t)(bj * 128 + j) * 8] = t0; pp[(size_t)(bj * 128 + 4 + j) * 8] = t1; } } }
;             return; }
;         bf16_t* base; size_t ld; int row0, col0, act;
;         if (pn < 12)      { base = (bf16_t*)(ws + WS_Q);  ld = DM;  row0 = u.pm * 256; col0 = (pn - 8) * 256;  act = 0; }
	ds_read_b128 v[166:169], v206 offset:49152
	ds_read_b128 v[170:173], v206 offset:50176
	ds_read_b128 v[174:177], v206 offset:51200
	ds_read_b128 v[178:181], v206 offset:52224
	ds_read_b128 v[182:185], v206 offset:53248
	ds_read_b128 v[186:189], v206 offset:54272
	ds_read_b128 v[190:193], v206 offset:55296
	ds_read_b128 v[194:197], v206 offset:56320
	global_load_lds_dwordx4 v[202:203], off
	v_lshl_add_u64 v[202:203], v[226:227], 0, s[58:59]
	s_mov_b32 m0, s90
	s_nop 0
	global_load_lds_dwordx4 v[202:203], off
	s_barrier
	s_waitcnt lgkmcnt(0)
	s_setprio 1
	s_waitcnt lgkmcnt(0)
	v_mfma_f32_16x16x32_bf16 v[56:59], v[150:153], v[166:169], v[56:59]
	v_mfma_f32_16x16x32_bf16 v[56:59], v[154:157], v[170:173], v[56:59]
	v_mfma_f32_16x16x32_bf16 v[52:55], v[162:165], v[170:173], v[52:55]
	v_mfma_f32_16x16x32_bf16 v[52:55], v[158:161], v[166:169], v[52:55]
	v_mfma_f32_16x16x32_bf16 v[36:39], v[158:161], v[174:177], v[36:39]
	v_mfma_f32_16x16x32_bf16 v[36:39], v[162:165], v[178:181], v[36:39]
	v_mfma_f32_16x16x32_bf16 v[40:43], v[154:157], v[178:181], v[40:43]
	v_mfma_f32_16x16x32_bf16 v[40:43], v[150:153], v[174:177], v[40:43]
	v_mfma_f32_16x16x32_bf16 v[24:27], v[150:153], v[182:185], v[24:27]
	v_mfma_f32_16x16x32_bf16 v[24:27], v[154:157], v[186:189], v[24:27]
	v_mfma_f32_16x16x32_bf16 v[20:23], v[162:165], v[186:189], v[20:23]
	v_mfma_f32_16x16x32_bf16 v[20:23], v[158:161], v[182:185], v[20:23]
	v_mfma_f32_16x16x32_bf16 v[4:7], v[158:161], v[190:193], v[4:7]
	v_mfma_f32_16x16x32_bf16 v[4:7], v[162:165], v[194:197], v[4:7]
	v_mfma_f32_16x16x32_bf16 v[8:11], v[154:157], v[194:197], v[8:11]
	v_mfma_f32_16x16x32_bf16 v[8:11], v[150:153], v[190:193], v[8:11]
	s_setprio 0
	s_barrier
	s_add_u32 s78, s78, 0x40080
	s_addc_u32 s79, s79, 0
	s_add_i32 s69, s71, s65
	s_mov_b32 m0, s69
	s_nop 0
	global_load_lds_dwordx4 v134, s[78:79]
	s_add_i32 m0, s69, 0x2000
	s_nop 0
	global_load_lds_dwordx4 v138, s[78:79]
	s_waitcnt vmcnt(6)
	s_barrier
	s_setprio 1
	v_mfma_f32_16x16x32_bf16 v[60:63], v[198:201], v[166:169], v[60:63]
	v_mfma_f32_16x16x32_bf16 v[60:63], v[210:213], v[170:173], v[60:63]
	v_mfma_f32_16x16x32_bf16 v[48:51], v[218:221], v[170:173], v[48:51]
	v_mfma_f32_16x16x32_bf16 v[48:51], v[214:217], v[166:169], v[48:51]
	v_mfma_f32_16x16x32_bf16 v[32:35], v[214:217], v[174:177], v[32:35]
	v_mfma_f32_16x16x32_bf16 v[32:35], v[218:221], v[178:181], v[32:35]
	v_mfma_f32_16x16x32_bf16 v[44:47], v[210:213], v[178:181], v[44:47]
	v_mfma_f32_16x16x32_bf16 v[44:47], v[198:201], v[174:177], v[44:47]
	v_mfma_f32_16x16x32_bf16 v[28:31], v[198:201], v[182:185], v[28:31]
	v_mfma_f32_16x16x32_bf16 v[28:31], v[210:213], v[186:189], v[28:31]
	v_mfma_f32_16x16x32_bf16 v[16:19], v[218:221], v[186:189], v[16:19]
	v_mfma_f32_16x16x32_bf16 v[16:19], v[214:217], v[182:185], v[16:19]
	v_mfma_f32_16x16x32_bf16 v[0:3], v[214:217], v[190:193], v[0:3]
	v_mfma_f32_16x16x32_bf16 v[0:3], v[218:221], v[194:197], v[0:3]
	v_mfma_f32_16x16x32_bf16 v[12:15], v[210:213], v[194:197], v[12:15]
	v_mfma_f32_16x16x32_bf16 v[12:15], v[198:201], v[190:193], v[12:15]
	s_setprio 0
	s_add_i32 s63, s63, 2
	s_add_u32 s6, s6, 0x100
	s_addc_u32 s7, s7, 0
	s_add_u32 s20, s20, 0x100
	s_addc_u32 s25, s25, 0
	s_cmp_gt_u32 s63, 13
	s_barrier
	s_cbranch_scc0 .LBB0_127
	s_nop 0
	s_nop 0
	s_nop 0
	s_nop 0
	s_nop 0
	s_nop 0
	s_nop 0
	s_nop 0
	s_nop 0
	s_nop 0
	s_nop 0
	s_nop 0
	s_nop 0
	s_nop 0
	s_nop 0
	s_nop 0
	s_cmp_gt_i32 s74, 7
	s_mov_b64 s[6:7], -1
	s_cbranch_scc0 .LBB0_188
	s_sub_i32 s25, s74, 17
	s_cmp_gt_u32 s25, 3
	s_cbranch_scc0 .LBB0_170
	s_lshl_b32 s69, s76, 8
	s_cmp_gt_u32 s74, 11
	s_cbranch_scc0 .LBB0_135
	s_cmp_eq_u32 s74, 12
	s_mov_b64 s[6:7], 0
	s_cbranch_scc1 .LBB0_134
	s_cmp_gt_u32 s74, 16
	s_cbranch_scc1 .LBB0_191
	s_lshl_b32 s20, s74, 8
	v_readlane_b32 s80, v254, 2
	s_addk_i32 s20, 0xf300
	s_mov_b64 s[78:79], 0x400
	s_mov_b64 s[82:83], -1
	s_mov_b32 s63, s69
	v_readlane_b32 s81, v254, 3
	s_andn2_b64 vcc, exec, s[6:7]
	s_cbranch_vccz .LBB0_136
	s_branch .LBB0_137

; #define PG8_STAGE(bufoff, gbase, voff) do { _Pragma("unroll") for (int _i = 0; _i < 2; ++_i) \
;         __builtin_amdgcn_global_load_lds((const unsigned*)((const char*)(gbase) + (voff)[_i]), (LAS unsigned*)(lds + (bufoff) + ldsw + _i * 8192), 16, 0, 0); } while (0)
; #define PG8_LDA(dst, b, h) do { _Pragma("unroll") for (int m = 0; m < 4; ++m) _Pragma("unroll") for (int k = 0; k < 2; ++k) dst[m][k] = *(const LAS bf16x8*)(lds + PG8_SA(b, h) + aoff + m * 2048 + k * 1024); } while (0)
; #define PG8_LDB(dst, b, h) do { _Pragma("unroll") for (int n = 0; n < 2; ++n) _Pragma("unroll") for (int k = 0; k < 2; ++k) dst[n][k] = *(const LAS bf16x8*)(lds + PG8_SB(b, h) + boff + n * 2048 + k * 1024); } while (0)
; #define PG8_MMA(ai, bj, At, Bt) do { __builtin_amdgcn_s_setprio(1); _Pragma("unroll") for (int m = 0; m < 4; ++m) _Pragma("unroll") for (int n = 0; n < 2; ++n) _Pragma("unroll") for (int k = 0; k < 2; ++k) \
;         acc[ai][bj][m][n] = __builtin_amdgcn_mfma_f32_16x16x32_bf16(Bt[n][k], At[m][k], acc[ai][bj][m][n], 0, 0, 0); __builtin_amdgcn_s_setprio(0); } while (0)
; #define PG8_WAIT_V(n) asm volatile("s_waitcnt vmcnt(" #n ")" ::: "memory")
; #define PG8_WAIT_L(n) asm volatile("s_waitcnt lgkmcnt(" #n ")" ::: "memory")
; #define PG8_BAR __builtin_amdgcn_s_barrier()
; #define PG8_SCHED __builtin_amdgcn_sched_barrier(0)
; template <class Epi, class Ptrs>
; __device__ __forceinline__ void gemm_phase(LAS unsigned char* lds, const int K, const StaticOrder& S, const Ptrs& P, const Epi& E) {
;     ...
;             PG8_LDB(B0, 0, 0); PG8_SCHED; PG8_LDA(At, 0, 0); PG8_STAGE(PG8_SA(1, 1), a1 + hstep, voffA);
;             PG8_WAIT_L(8); PG8_BAR; PG8_WAIT_L(0); PG8_MMA(0, 0, At, B0); PG8_BAR; PG8_SCHED;
;             PG8_LDB(B1, 0, 1); PG8_STAGE(PG8_SB(0, 0), b2, voffB);
;             PG8_BAR; PG8_WAIT_L(0); PG8_MMA(0, 1, At, B1); PG8_BAR;
;             PG8_LDA(At, 0, 1); PG8_STAGE(PG8_SA(0, 0), a2, voffA);
;             PG8_BAR; PG8_WAIT_L(0); PG8_MMA(1, 0, At, B0); PG8_BAR; PG8_SCHED;
;             PG8_STAGE(PG8_SB(0, 1), b2 + hstep, voffB);
;             PG8_WAIT_V(6); PG8_BAR; PG8_MMA(1, 1, At, B1); PG8_BAR;
.LBB0_353:
	ds_read_b128 v[128:131], v207
	ds_read_b128 v[132:135], v207 offset:1024
	ds_read_b128 v[136:139], v207 offset:2048
	ds_read_b128 v[140:143], v207 offset:3072
	s_add_u32 s42, s38, 0xfffc0080
	s_addc_u32 s43, s39, -1
	s_cmp_eq_u32 s41, 12
	s_cselect_b32 s45, s1, s43
	s_cselect_b32 s44, s0, s42
	s_cselect_b32 s43, s25, s23
	s_cselect_b32 s42, s24, s21
	s_add_i32 m0, s54, 0xc000
	ds_read_b128 v[144:147], v209
	ds_read_b128 v[148:151], v209 offset:1024
	ds_read_b128 v[152:155], v209 offset:2048
	ds_read_b128 v[156:159], v209 offset:3072
	ds_read_b128 v[160:163], v209 offset:4096
	ds_read_b128 v[164:167], v209 offset:5120
	ds_read_b128 v[168:171], v209 offset:6144
	ds_read_b128 v[172:175], v209 offset:7168
	global_load_lds_dwordx4 v184, s[38:39]
	s_add_i32 m0, s54, 0xe000
	s_nop 0
	global_load_lds_dwordx4 v186, s[38:39]
	s_waitcnt lgkmcnt(8)
	s_barrier
	s_waitcnt lgkmcnt(0)
	s_setprio 1
	s_waitcnt lgkmcnt(0)
	v_mfma_f32_16x16x32_bf16 v[124:127], v[128:131], v[144:147], v[124:127]
	v_mfma_f32_16x16x32_bf16 v[124:127], v[132:135], v[148:151], v[124:127]
	v_mfma_f32_16x16x32_bf16 v[120:123], v[140:143], v[148:151], v[120:123]
	v_mfma_f32_16x16x32_bf16 v[120:123], v[136:139], v[144:147], v[120:123]
	v_mfma_f32_16x16x32_bf16 v[104:107], v[136:139], v[152:155], v[104:107]
	v_mfma_f32_16x16x32_bf16 v[104:107], v[140:143], v[156:159], v[104:107]
	v_mfma_f32_16x16x32_bf16 v[108:111], v[132:135], v[156:159], v[108:111]
	v_mfma_f32_16x16x32_bf16 v[108:111], v[128:131], v[152:155], v[108:111]
	v_mfma_f32_16x16x32_bf16 v[92:95], v[128:131], v[160:163], v[92:95]
	v_mfma_f32_16x16x32_bf16 v[92:95], v[132:135], v[164:167], v[92:95]
	v_mfma_f32_16x16x32_bf16 v[88:91], v[140:143], v[164:167], v[88:91]
	v_mfma_f32_16x16x32_bf16 v[88:91], v[136:139], v[160:163], v[88:91]
	v_mfma_f32_16x16x32_bf16 v[72:75], v[136:139], v[168:171], v[72:75]
	v_mfma_f32_16x16x32_bf16 v[72:75], v[140:143], v[172:175], v[72:75]
	v_mfma_f32_16x16x32_bf16 v[76:79], v[132:135], v[172:175], v[76:79]
	v_mfma_f32_16x16x32_bf16 v[76:79], v[128:131], v[168:171], v[76:79]
	s_setprio 0
	s_barrier
	s_add_i32 s69, s66, s51
	v_lshl_add_u64 v[216:217], s[42:43], 0, v[178:179]
	s_mov_b32 m0, s69
	ds_read_b128 v[192:195], v210
	ds_read_b128 v[196:199], v210 offset:1024
	ds_read_b128 v[200:203], v210 offset:2048
	ds_read_b128 v[212:215], v210 offset:3072
	global_load_lds_dwordx4 v[216:217], off
	v_lshl_add_u64 v[218:219], s[42:43], 0, v[182:183]
	s_add_i32 m0, s69, 0x2000
	s_nop 0
	global_load_lds_dwordx4 v[218:219], off
	s_barrier
	s_waitcnt lgkmcnt(0)
	s_setprio 1
	s_waitcnt lgkmcnt(0)
	v_mfma_f32_16x16x32_bf16 v[116:119], v[192:195], v[144:147], v[116:119]
	v_mfma_f32_16x16x32_bf16 v[116:119], v[196:199], v[148:151], v[116:119]
	v_mfma_f32_16x16x32_bf16 v[112:115], v[212:215], v[148:151], v[112:115]
	v_mfma_f32_16x16x32_bf16 v[112:115], v[200:203], v[144:147], v[112:115]
	v_mfma_f32_16x16x32_bf16 v[96:99], v[200:203], v[152:155], v[96:99]
	v_mfma_f32_16x16x32_bf16 v[96:99], v[212:215], v[156:159], v[96:99]
	v_mfma_f32_16x16x32_bf16 v[100:103], v[196:199], v[156:159], v[100:103]
	v_mfma_f32_16x16x32_bf16 v[100:103], v[192:195], v[152:155], v[100:103]
	v_mfma_f32_16x16x32_bf16 v[84:87], v[192:195], v[160:163], v[84:87]
	v_mfma_f32_16x16x32_bf16 v[84:87], v[196:199], v[164:167], v[84:87]
	v_mfma_f32_16x16x32_bf16 v[80:83], v[212:215], v[164:167], v[80:83]
	v_mfma_f32_16x16x32_bf16 v[80:83], v[200:203], v[160:163], v[80:83]
	v_mfma_f32_16x16x32_bf16 v[64:67], v[200:203], v[168:171], v[64:67]
	v_mfma_f32_16x16x32_bf16 v[64:67], v[212:215], v[172:175], v[64:67]
	v_mfma_f32_16x16x32_bf16 v[68:71], v[196:199], v[172:175], v[68:71]
	v_mfma_f32_16x16x32_bf16 v[68:71], v[192:195], v[168:171], v[68:71]
	s_setprio 0
	s_mov_b32 m0, s54
	v_lshl_add_u64 v[220:221], s[44:45], 0, v[176:177]
	s_barrier
	ds_read_b128 v[144:147], v209 offset:16384
	ds_read_b128 v[148:151], v209 offset:17408
	ds_read_b128 v[152:155], v209 offset:18432
	ds_read_b128 v[156:159], v209 offset:19456
	ds_read_b128 v[160:163], v209 offset:20480
	ds_read_b128 v[164:167], v209 offset:21504
	ds_read_b128 v[168:171], v209 offset:22528
	ds_read_b128 v[172:175], v209 offset:23552
	global_load_lds_dwordx4 v[220:221], off
	v_lshl_add_u64 v[222:223], s[44:45], 0, v[180:181]
	s_mov_b32 m0, s55
	s_nop 0
	global_load_lds_dwordx4 v[222:223], off
	s_barrier
	s_waitcnt lgkmcnt(0)
	s_setprio 1
	s_waitcnt lgkmcnt(0)
	v_mfma_f32_16x16x32_bf16 v[60:63], v[128:131], v[144:147], v[60:63]
	v_mfma_f32_16x16x32_bf16 v[60:63], v[132:135], v[148:151], v[60:63]
	v_mfma_f32_16x16x32_bf16 v[56:59], v[140:143], v[148:151], v[56:59]
	v_mfma_f32_16x16x32_bf16 v[56:59], v[136:139], v[144:147], v[56:59]
	v_mfma_f32_16x16x32_bf16 v[40:43], v[136:139], v[152:155], v[40:43]
	v_mfma_f32_16x16x32_bf16 v[40:43], v[140:143], v[156:159], v[40:43]
	v_mfma_f32_16x16x32_bf16 v[44:47], v[132:135], v[156:159], v[44:47]
	v_mfma_f32_16x16x32_bf16 v[44:47], v[128:131], v[152:155], v[44:47]
	v_mfma_f32_16x16x32_bf16 v[28:31], v[128:131], v[160:163], v[28:31]
	v_mfma_f32_16x16x32_bf16 v[28:31], v[132:135], v[164:167], v[28:31]
	v_mfma_f32_16x16x32_bf16 v[24:27], v[140:143], v[164:167], v[24:27]
	v_mfma_f32_16x16x32_bf16 v[24:27], v[136:139], v[160:163], v[24:27]
	v_mfma_f32_16x16x32_bf16 v[8:11], v[136:139], v[168:171], v[8:11]
	v_mfma_f32_16x16x32_bf16 v[8:11], v[140:143], v[172:175], v[8:11]
	v_mfma_f32_16x16x32_bf16 v[12:15], v[132:135], v[172:175], v[12:15]
	v_mfma_f32_16x16x32_bf16 v[12:15], v[128:131], v[168:171], v[12:15]
	s_setprio 0
	s_barrier
	s_add_u32 s70, s42, 0x40000
	s_addc_u32 s71, s43, 0
	s_add_i32 s69, s67, s51
	s_mov_b32 m0, s69
	s_nop 0
	global_load_lds_dwordx4 v178, s[70:71]
	s_add_i32 m0, s69, 0x2000
	s_nop 0
	global_load_lds_dwordx4 v182, s[70:71]
	s_waitcnt vmcnt(6)
	s_barrier
; #define PG8_STAGE(bufoff, gbase, voff) do { _Pragma("unroll") for (int _i = 0; _i < 2; ++_i) \
;         __builtin_amdgcn_global_load_lds((const unsigned*)((const char*)(gbase) + (voff)[_i]), (LAS unsigned*)(lds + (bufoff) + ldsw + _i * 8192), 16, 0, 0); } while (0)
; #define PG8_LDA(dst, b, h) do { _Pragma("unroll") for (int m = 0; m < 4; ++m) _Pragma("unroll") for (int k = 0; k < 2; ++k) dst[m][k] = *(const LAS bf16x8*)(lds + PG8_SA(b, h) + aoff + m * 2048 + k * 1024); } while (0)
; #define PG8_LDB(dst, b, h) do { _Pragma("unroll") for (int n = 0; n < 2; ++n) _Pragma("unroll") for (int k = 0; k < 2; ++k) dst[n][k] = *(const LAS bf16x8*)(lds + PG8_SB(b, h) + boff + n * 2048 + k * 1024); } while (0)
; #define PG8_MMA(ai, bj, At, Bt) do { __builtin_amdgcn_s_setprio(1); _Pragma("unroll") for (int m = 0; m < 4; ++m) _Pragma("unroll") for (int n = 0; n < 2; ++n) _Pragma("unroll") for (int k = 0; k < 2; ++k) \
;         acc[ai][bj][m][n] = __builtin_amdgcn_mfma_f32_16x16x32_bf16(Bt[n][k], At[m][k], acc[ai][bj][m][n], 0, 0, 0); __builtin_amdgcn_s_setprio(0); } while (0)
; #define PG8_WAIT_V(n) asm volatile("s_waitcnt vmcnt(" #n ")" ::: "memory")
; #define PG8_WAIT_L(n) asm volatile("s_waitcnt lgkmcnt(" #n ")" ::: "memory")
; #define PG8_BAR __builtin_amdgcn_s_barrier()
; #define PG8_SCHED __builtin_amdgcn_sched_barrier(0)
; template <class Epi, class Ptrs>
; __device__ __forceinline__ void gemm_phase(LAS unsigned char* lds, const int K, const StaticOrder& S, const Ptrs& P, const Epi& E) {
;     ...
;             PG8_WAIT_V(6); PG8_BAR; PG8_MMA(1, 1, At, B1); PG8_BAR;
;             PG8_LDB(B0, 1, 0); PG8_SCHED; PG8_LDA(At, 1, 0); PG8_STAGE(PG8_SA(0, 1), a2 + hstep, voffA);
;             PG8_WAIT_L(8); PG8_BAR; PG8_WAIT_L(0); PG8_MMA(0, 0, At, B0); PG8_BAR; PG8_SCHED;
;             PG8_LDB(B1, 1, 1); PG8_STAGE(PG8_SB(1, 0), b3, voffB);
;             PG8_BAR; PG8_WAIT_L(0); PG8_MMA(0, 1, At, B1); PG8_BAR;
;             PG8_LDA(At, 1, 1); PG8_STAGE(PG8_SA(1, 0), a3, voffA);
	s_setprio 1
	v_mfma_f32_16x16x32_bf16 v[52:55], v[192:195], v[144:147], v[52:55]
	v_mfma_f32_16x16x32_bf16 v[52:55], v[196:199], v[148:151], v[52:55]
	v_mfma_f32_16x16x32_bf16 v[48:51], v[212:215], v[148:151], v[48:51]
	v_mfma_f32_16x16x32_bf16 v[48:51], v[200:203], v[144:147], v[48:51]
	v_mfma_f32_16x16x32_bf16 v[32:35], v[200:203], v[152:155], v[32:35]
	v_mfma_f32_16x16x32_bf16 v[32:35], v[212:215], v[156:159], v[32:35]
	v_mfma_f32_16x16x32_bf16 v[36:39], v[196:199], v[156:159], v[36:39]
	v_mfma_f32_16x16x32_bf16 v[36:39], v[192:195], v[152:155], v[36:39]
	v_mfma_f32_16x16x32_bf16 v[20:23], v[192:195], v[160:163], v[20:23]
	v_mfma_f32_16x16x32_bf16 v[20:23], v[196:199], v[164:167], v[20:23]
	v_mfma_f32_16x16x32_bf16 v[16:19], v[212:215], v[164:167], v[16:19]
	v_mfma_f32_16x16x32_bf16 v[16:19], v[200:203], v[160:163], v[16:19]
	v_mfma_f32_16x16x32_bf16 v[0:3], v[200:203], v[168:171], v[0:3]
	v_mfma_f32_16x16x32_bf16 v[0:3], v[212:215], v[172:175], v[0:3]
	v_mfma_f32_16x16x32_bf16 v[4:7], v[196:199], v[172:175], v[4:7]
	v_mfma_f32_16x16x32_bf16 v[4:7], v[192:195], v[168:171], v[4:7]
	s_setprio 0
	s_add_i32 s69, 0, 0x18000
	v_add_u32_e32 v140, s69, v205
	s_barrier
	ds_read_b128 v[128:131], v140
	ds_read_b128 v[132:135], v140 offset:1024
	ds_read_b128 v[136:139], v140 offset:2048
	ds_read_b128 v[140:143], v140 offset:3072
	s_add_u32 s44, s44, 0x40000
	s_addc_u32 s45, s45, 0
	s_mov_b32 m0, s56
	ds_read_b128 v[144:147], v209 offset:32768
	ds_read_b128 v[148:151], v209 offset:33792
	ds_read_b128 v[152:155], v209 offset:34816
	ds_read_b128 v[156:159], v209 offset:35840
	ds_read_b128 v[160:163], v209 offset:36864
	ds_read_b128 v[164:167], v209 offset:37888
	ds_read_b128 v[168:171], v209 offset:38912
	ds_read_b128 v[172:175], v209 offset:39936
	global_load_lds_dwordx4 v176, s[44:45]
	s_mov_b32 m0, s57
	s_nop 0
	global_load_lds_dwordx4 v180, s[44:45]
	s_waitcnt lgkmcnt(8)
	s_barrier
	s_waitcnt lgkmcnt(0)
	s_setprio 1
	s_waitcnt lgkmcnt(0)
	v_mfma_f32_16x16x32_bf16 v[124:127], v[128:131], v[144:147], v[124:127]
	v_mfma_f32_16x16x32_bf16 v[124:127], v[132:135], v[148:151], v[124:127]
	v_mfma_f32_16x16x32_bf16 v[120:123], v[140:143], v[148:151], v[120:123]
	v_mfma_f32_16x16x32_bf16 v[120:123], v[136:139], v[144:147], v[120:123]
	v_mfma_f32_16x16x32_bf16 v[104:107], v[136:139], v[152:155], v[104:107]
	v_mfma_f32_16x16x32_bf16 v[104:107], v[140:143], v[156:159], v[104:107]
	v_mfma_f32_16x16x32_bf16 v[108:111], v[132:135], v[156:159], v[108:111]
	v_mfma_f32_16x16x32_bf16 v[108:111], v[128:131], v[152:155], v[108:111]
	v_mfma_f32_16x16x32_bf16 v[92:95], v[128:131], v[160:163], v[92:95]
	v_mfma_f32_16x16x32_bf16 v[92:95], v[132:135], v[164:167], v[92:95]
	v_mfma_f32_16x16x32_bf16 v[88:91], v[140:143], v[164:167], v[88:91]
	v_mfma_f32_16x16x32_bf16 v[88:91], v[136:139], v[160:163], v[88:91]
	v_mfma_f32_16x16x32_bf16 v[72:75], v[136:139], v[168:171], v[72:75]
	v_mfma_f32_16x16x32_bf16 v[72:75], v[140:143], v[172:175], v[72:75]
	v_mfma_f32_16x16x32_bf16 v[76:79], v[132:135], v[172:175], v[76:79]
	v_mfma_f32_16x16x32_bf16 v[76:79], v[128:131], v[168:171], v[76:79]
	s_setprio 0
	s_barrier
	s_add_i32 s44, 0, 0x1c000
	s_add_i32 s45, s69, s51
	v_add_u32_e32 v211, s44, v205
	v_lshl_add_u64 v[216:217], v[216:217], 0, s[18:19]
	s_mov_b32 m0, s45
	ds_read_b128 v[192:195], v211
	ds_read_b128 v[196:199], v211 offset:1024
	ds_read_b128 v[200:203], v211 offset:2048
	ds_read_b128 v[212:215], v211 offset:3072
	global_load_lds_dwordx4 v[216:217], off
	v_lshl_add_u64 v[216:217], v[218:219], 0, s[18:19]
	s_add_i32 m0, s45, 0x2000
	s_nop 0
	global_load_lds_dwordx4 v[216:217], off
	s_barrier
	s_waitcnt lgkmcnt(0)
	s_setprio 1
	s_waitcnt lgkmcnt(0)
	v_mfma_f32_16x16x32_bf16 v[116:119], v[192:195], v[144:147], v[116:119]
	v_mfma_f32_16x16x32_bf16 v[116:119], v[196:199], v[148:151], v[116:119]
	v_mfma_f32_16x16x32_bf16 v[112:115], v[212:215], v[148:151], v[112:115]
	v_mfma_f32_16x16x32_bf16 v[112:115], v[200:203], v[144:147], v[112:115]
	v_mfma_f32_16x16x32_bf16 v[96:99], v[200:203], v[152:155], v[96:99]
	v_mfma_f32_16x16x32_bf16 v[96:99], v[212:215], v[156:159], v[96:99]
	v_mfma_f32_16x16x32_bf16 v[100:103], v[196:199], v[156:159], v[100:103]
	v_mfma_f32_16x16x32_bf16 v[100:103], v[192:195], v[152:155], v[100:103]
	v_mfma_f32_16x16x32_bf16 v[84:87], v[192:195], v[160:163], v[84:87]
	v_mfma_f32_16x16x32_bf16 v[84:87], v[196:199], v[164:167], v[84:87]
	v_mfma_f32_16x16x32_bf16 v[80:83], v[212:215], v[164:167], v[80:83]
	v_mfma_f32_16x16x32_bf16 v[80:83], v[200:203], v[160:163], v[80:83]
	v_mfma_f32_16x16x32_bf16 v[64:67], v[200:203], v[168:171], v[64:67]
	v_mfma_f32_16x16x32_bf16 v[64:67], v[212:215], v[172:175], v[64:67]
	v_mfma_f32_16x16x32_bf16 v[68:71], v[196:199], v[172:175], v[68:71]
	v_mfma_f32_16x16x32_bf16 v[68:71], v[192:195], v[168:171], v[68:71]
	s_setprio 0
	s_mov_b32 m0, s63
	v_lshl_add_u64 v[216:217], v[220:221], 0, s[18:19]
	s_barrier
	ds_read_b128 v[144:147], v209 offset:49152
	ds_read_b128 v[148:151], v209 offset:50176
	ds_read_b128 v[152:155], v209 offset:51200
	ds_read_b128 v[156:159], v209 offset:52224
	ds_read_b128 v[160:163], v209 offset:53248
	ds_read_b128 v[164:167], v209 offset:54272
	ds_read_b128 v[168:171], v209 offset:55296
	ds_read_b128 v[172:175], v209 offset:56320
	global_load_lds_dwordx4 v[216:217], off
	v_lshl_add_u64 v[216:217], v[222:223], 0, s[18:19]
	s_mov_b32 m0, s64
	s_nop 0
	global_load_lds_dwordx4 v[216:217], off
	s_barrier
; __device__ __forceinline__ unsigned cvt_pk_bf16(float lo, float hi) { unsigned r; asm volatile("v_cvt_pk_bf16_f32 %0, %1, %2" : "=v"(r) : "v"(lo), "v"(hi)); return r; }
; __device__ __forceinline__ float x16_sum(float x) { auto s = __builtin_amdgcn_permlane16_swap(__float_as_uint(x), __float_as_uint(x), false, false); return __uint_as_float(s[0]) + __uint_as_float(s[1]); }
; #define PG8_WAIT_V(n) asm volatile("s_waitcnt vmcnt(" #n ")" ::: "memory")
; template <class Epi, class Ptrs>
; __device__ __forceinline__ void gemm_phase(LAS unsigned char* lds, const int K, const StaticOrder& S, const Ptrs& P, const Epi& E) {
;     ...
;             PG8_BAR; PG8_WAIT_L(0); PG8_MMA(1, 0, At, B0); PG8_BAR; PG8_SCHED;
;             PG8_STAGE(PG8_SB(1, 1), b3 + hstep, voffB);
;             PG8_WAIT_V(6); PG8_BAR; PG8_MMA(1, 1, At, B1); PG8_BAR;
;         }
;     __device__ __forceinline__ void operator()(const f32x4 (&acc)[2][2][4][2], const Unit& u, int ui, int wr, int wc, int fr, int fq) const {
;         const int row0 = u.pm * 256 + wr * 64 + fr, col0 = u.pn * 256 + wc * 32 + 8 * fq;
;         const float* xb0 = (u.pm * 256 < MP) ? xp : xs - (size_t)MP * DM;
; #pragma unroll
;         for (int ai = 0; ai < 2; ++ai) {
;             f32x4 xv[4][2][2];
; #pragma unroll
;             for (int m = 0; m < 4; ++m)
; #pragma unroll
;                 for (int bj = 0; bj < 2; ++bj) { const float* p = xb0 + (size_t)(row0 + ai * 128 + m * 16) * DM + col0 + bj * 128; xv[m][bj][0] = *(const f32x4*)p; xv[m][bj][1] = *(const f32x4*)(p + 4); }
; #pragma unroll
;             for (int m = 0; m < 4; ++m) { const int row = row0 + ai * 128 + m * 16; const size_t off = (size_t)row * DM + col0; float ss = 0.f;
; #pragma unroll
;                 for (int bj = 0; bj < 2; ++bj) {
;                     const f32x4 v0 = acc[ai][bj][m][0] + xv[m][bj][0], v1 = acc[ai][bj][m][1] + xv[m][bj][1];
;                     u32x4 w; w.x = cvt_pk_bf16(v0[0], v0[1]); w.y = cvt_pk_bf16(v0[2], v0[3]); w.z = cvt_pk_bf16(v1[0], v1[1]); w.w = cvt_pk_bf16(v1[2], v1[3]);
;                     *(u32x4*)(xb + off + bj * 128) = w;
;                     ss += (v0[0] * v0[0] + v0[1] * v0[1]) + (v0[2] * v0[2] + v0[3] * v0[3]) + (v1[0] * v1[0] + v1[1] * v1[1]) + (v1[2] * v1[2] + v1[3] * v1[3]); }
;                 ss = x32_sum(x16_sum(ss));
;                 if (fq == 0) part[(size_t)row * 16 + u.pn * 4 + wc] = ss; }
	s_waitcnt lgkmcnt(0)
	s_setprio 1
	s_waitcnt lgkmcnt(0)
	v_mfma_f32_16x16x32_bf16 v[60:63], v[128:131], v[144:147], v[60:63]
	v_mfma_f32_16x16x32_bf16 v[60:63], v[132:135], v[148:151], v[60:63]
	v_mfma_f32_16x16x32_bf16 v[56:59], v[140:143], v[148:151], v[56:59]
	v_mfma_f32_16x16x32_bf16 v[56:59], v[136:139], v[144:147], v[56:59]
	v_mfma_f32_16x16x32_bf16 v[40:43], v[136:139], v[152:155], v[40:43]
	v_mfma_f32_16x16x32_bf16 v[40:43], v[140:143], v[156:159], v[40:43]
	v_mfma_f32_16x16x32_bf16 v[44:47], v[132:135], v[156:159], v[44:47]
	v_mfma_f32_16x16x32_bf16 v[44:47], v[128:131], v[152:155], v[44:47]
	v_mfma_f32_16x16x32_bf16 v[28:31], v[128:131], v[160:163], v[28:31]
	v_mfma_f32_16x16x32_bf16 v[28:31], v[132:135], v[164:167], v[28:31]
	v_mfma_f32_16x16x32_bf16 v[24:27], v[140:143], v[164:167], v[24:27]
	v_mfma_f32_16x16x32_bf16 v[24:27], v[136:139], v[160:163], v[24:27]
	v_mfma_f32_16x16x32_bf16 v[8:11], v[136:139], v[168:171], v[8:11]
	v_mfma_f32_16x16x32_bf16 v[8:11], v[140:143], v[172:175], v[8:11]
	v_mfma_f32_16x16x32_bf16 v[12:15], v[132:135], v[172:175], v[12:15]
	v_mfma_f32_16x16x32_bf16 v[12:15], v[128:131], v[168:171], v[12:15]
	s_setprio 0
	s_barrier
	s_add_u32 s42, s42, 0x40080
	s_addc_u32 s43, s43, 0
	s_add_i32 s44, s44, s51
	s_mov_b32 m0, s44
	s_nop 0
	global_load_lds_dwordx4 v178, s[42:43]
	s_add_i32 m0, s44, 0x2000
	s_nop 0
	global_load_lds_dwordx4 v182, s[42:43]
	s_waitcnt vmcnt(6)
	s_barrier
	s_setprio 1
	v_mfma_f32_16x16x32_bf16 v[52:55], v[192:195], v[144:147], v[52:55]
	v_mfma_f32_16x16x32_bf16 v[52:55], v[196:199], v[148:151], v[52:55]
	v_mfma_f32_16x16x32_bf16 v[48:51], v[212:215], v[148:151], v[48:51]
	v_mfma_f32_16x16x32_bf16 v[48:51], v[200:203], v[144:147], v[48:51]
	v_mfma_f32_16x16x32_bf16 v[32:35], v[200:203], v[152:155], v[32:35]
	v_mfma_f32_16x16x32_bf16 v[32:35], v[212:215], v[156:159], v[32:35]
	v_mfma_f32_16x16x32_bf16 v[36:39], v[196:199], v[156:159], v[36:39]
	v_mfma_f32_16x16x32_bf16 v[36:39], v[192:195], v[152:155], v[36:39]
	v_mfma_f32_16x16x32_bf16 v[20:23], v[192:195], v[160:163], v[20:23]
	v_mfma_f32_16x16x32_bf16 v[20:23], v[196:199], v[164:167], v[20:23]
	v_mfma_f32_16x16x32_bf16 v[16:19], v[212:215], v[164:167], v[16:19]
	v_mfma_f32_16x16x32_bf16 v[16:19], v[200:203], v[160:163], v[16:19]
	v_mfma_f32_16x16x32_bf16 v[0:3], v[200:203], v[168:171], v[0:3]
	v_mfma_f32_16x16x32_bf16 v[0:3], v[212:215], v[172:175], v[0:3]
	v_mfma_f32_16x16x32_bf16 v[4:7], v[196:199], v[172:175], v[4:7]
	v_mfma_f32_16x16x32_bf16 v[4:7], v[192:195], v[168:171], v[4:7]
	s_setprio 0
	s_add_i32 s41, s41, 2
	s_add_u32 s38, s38, 0x100
	s_addc_u32 s39, s39, 0
	s_add_u32 s21, s21, 0x100
	s_addc_u32 s23, s23, 0
	s_cmp_gt_u32 s41, 13
	s_barrier
	s_cbranch_scc0 .LBB0_353
	s_nop 0
	s_nop 0
	s_nop 0
	s_nop 0
	s_nop 0
	s_nop 0
	s_nop 0
	s_nop 0
	s_nop 0
	s_nop 0
	s_nop 0
	s_nop 0
	s_nop 0
	s_nop 0
	s_nop 0
	s_nop 0
	s_cmpk_lt_i32 s40, 0x80
	v_lshl_add_u32 v194, s40, 8, v204
	v_lshl_or_b32 v192, s12, 8, v206
	s_cselect_b32 s21, s37, s61
	s_cselect_b32 s23, s36, s60
	v_mov_b32_e32 v128, s23
	v_mov_b32_e32 v129, s21
	v_ashrrev_i32_e32 v193, 31, v192
	v_ashrrev_i32_e32 v195, 31, v194
	v_lshl_add_u64 v[196:197], v[192:193], 2, v[128:129]
	v_lshlrev_b64 v[128:129], 12, v[194:195]
	v_or_b32_e32 v202, 16, v194
	v_or_b32_e32 v200, 32, v194
	v_or_b32_e32 v198, 48, v194
	v_lshl_add_u64 v[128:129], v[196:197], 0, v[128:129]
	v_ashrrev_i32_e32 v203, 31, v202
	v_ashrrev_i32_e32 v201, 31, v200
	v_ashrrev_i32_e32 v199, 31, v198
	global_load_dwordx4 v[212:215], v[128:129], off
	global_load_dwordx4 v[216:219], v[128:129], off offset:16
	global_load_dwordx4 v[220:223], v[128:129], off offset:512
	global_load_dwordx4 v[224:227], v[128:129], off offset:528
	v_lshlrev_b64 v[128:129], 12, v[202:203]
	v_lshlrev_b64 v[130:131], 12, v[200:201]
	v_lshlrev_b64 v[132:133], 12, v[198:199]
	v_lshl_add_u64 v[128:129], v[196:197], 0, v[128:129]
	v_lshl_add_u64 v[130:131], v[196:197], 0, v[130:131]
	v_lshl_add_u64 v[132:133], v[196:197], 0, v[132:133]
	global_load_dwordx4 v[168:171], v[128:129], off offset:16
	global_load_dwordx4 v[172:175], v[128:129], off
	global_load_dwordx4 v[160:163], v[128:129], off offset:528
	global_load_dwordx4 v[164:167], v[128:129], off offset:512
	global_load_dwordx4 v[152:155], v[130:131], off offset:16
	global_load_dwordx4 v[156:159], v[130:131], off
	global_load_dwordx4 v[144:147], v[130:131], off offset:528
	global_load_dwordx4 v[148:151], v[130:131], off offset:512
	global_load_dwordx4 v[136:139], v[132:133], off offset:16
	global_load_dwordx4 v[140:143], v[132:133], off
	s_nop 0
	global_load_dwordx4 v[128:131], v[132:133], off offset:528
	s_nop 0
	global_load_dwordx4 v[132:135], v[132:133], off offset:512
	v_lshlrev_b64 v[228:229], 11, v[194:195]
	v_lshl_add_u64 v[228:229], s[14:15], 0, v[228:229]
	v_lshl_add_u64 v[228:229], v[192:193], 1, v[228:229]
	s_lshl_b32 s38, s12, 2
	s_ashr_i32 s39, s38, 31
	s_waitcnt vmcnt(0)
	v_pk_add_f32 v[126:127], v[126:127], v[214:215]
	v_pk_add_f32 v[124:125], v[124:125], v[212:213]
	v_pk_add_f32 v[118:119], v[118:119], v[222:223]
	v_pk_add_f32 v[116:117], v[116:117], v[220:221]
	v_pk_add_f32 v[120:121], v[120:121], v[216:217]
	v_pk_add_f32 v[214:215], v[112:113], v[224:225]
	v_cvt_pk_bf16_f32 v112, v124, v125
	v_cvt_pk_bf16_f32 v113, v126, v127
	v_mul_f32_e32 v125, v125, v125
	v_mul_f32_e32 v127, v127, v127
	v_mul_f32_e32 v211, v117, v117
	v_mul_f32_e32 v216, v119, v119
	v_pk_add_f32 v[122:123], v[122:123], v[218:219]
	v_pk_add_f32 v[212:213], v[114:115], v[226:227]
	v_cvt_pk_bf16_f32 v114, v120, v121
	v_cvt_pk_bf16_f32 v115, v122, v123
	v_mul_f32_e32 v121, v121, v121
	v_mul_f32_e32 v217, v215, v215
	global_store_dwordx4 v[228:229], v[112:115], off
	v_fmac_f32_e32 v125, v124, v124
	v_fmac_f32_e32 v127, v126, v126
	v_cvt_pk_bf16_f32 v112, v116, v117
	v_fmac_f32_e32 v211, v116, v116
	v_fmac_f32_e32 v216, v118, v118
	v_mul_f32_e32 v123, v123, v123
	v_mul_f32_e32 v218, v213, v213
	v_fmac_f32_e32 v121, v120, v120
	v_cvt_pk_bf16_f32 v113, v118, v119
	v_cvt_pk_bf16_f32 v114, v214, v215
	v_cvt_pk_bf16_f32 v115, v212, v213
	v_fmac_f32_e32 v217, v214, v214
	v_add_f32_e32 v116, v125, v127
	global_store_dwordx4 v[228:229], v[112:115], off offset:256
	v_fmac_f32_e32 v123, v122, v122
	v_fmac_f32_e32 v218, v212, v212
	v_add_f32_e32 v112, v211, v216
	v_add_f32_e32 v113, v116, v121
	v_add_f32_e32 v112, v112, v217
	v_add_f32_e32 v113, v123, v113
	v_add_f32_e32 v112, v218, v112
	v_add_f32_e32 v112, v113, v112
	v_mov_b32_e32 v113, v112
	s_nop 1
	v_permlane16_swap_b32_e32 v112, v113
	v_add_f32_e32 v112, v112, v113
	v_mov_b32_e32 v113, v112
	s_nop 1
	v_permlane32_swap_b32_e32 v112, v113
	s_and_saveexec_b64 s[40:41], s[6:7]
	s_cbranch_execz .LBB0_356
	v_lshlrev_b64 v[114:115], 6, v[194:195]
	v_lshl_add_u64 v[114:115], s[16:17], 0, v[114:115]
	v_lshl_add_u64 v[114:115], s[38:39], 2, v[114:115]
	s_lshl_b32 s12, s62, 2
	v_lshl_add_u64 v[114:115], v[114:115], 0, s[12:13]
	v_add_f32_e32 v112, v112, v113
	global_store_dword v[114:115], v112, off

; #define PG8_STAGE(bufoff, gbase, voff) do { _Pragma("unroll") for (int _i = 0; _i < 2; ++_i) \
;         __builtin_amdgcn_global_load_lds((const unsigned*)((const char*)(gbase) + (voff)[_i]), (LAS unsigned*)(lds + (bufoff) + ldsw + _i * 8192), 16, 0, 0); } while (0)
; #define PG8_LDA(dst, b, h) do { _Pragma("unroll") for (int m = 0; m < 4; ++m) _Pragma("unroll") for (int k = 0; k < 2; ++k) dst[m][k] = *(const LAS bf16x8*)(lds + PG8_SA(b, h) + aoff + m * 2048 + k * 1024); } while (0)
; #define PG8_LDB(dst, b, h) do { _Pragma("unroll") for (int n = 0; n < 2; ++n) _Pragma("unroll") for (int k = 0; k < 2; ++k) dst[n][k] = *(const LAS bf16x8*)(lds + PG8_SB(b, h) + boff + n * 2048 + k * 1024); } while (0)
; #define PG8_MMA(ai, bj, At, Bt) do { __builtin_amdgcn_s_setprio(1); _Pragma("unroll") for (int m = 0; m < 4; ++m) _Pragma("unroll") for (int n = 0; n < 2; ++n) _Pragma("unroll") for (int k = 0; k < 2; ++k) \
;         acc[ai][bj][m][n] = __builtin_amdgcn_mfma_f32_16x16x32_bf16(Bt[n][k], At[m][k], acc[ai][bj][m][n], 0, 0, 0); __builtin_amdgcn_s_setprio(0); } while (0)
; #define PG8_WAIT_L(n) asm volatile("s_waitcnt lgkmcnt(" #n ")" ::: "memory")
; #define PG8_BAR __builtin_amdgcn_s_barrier()
; #define PG8_SCHED __builtin_amdgcn_sched_barrier(0)
; template <class Epi, class Ptrs>
; __device__ __forceinline__ void gemm_phase(LAS unsigned char* lds, const int K, const StaticOrder& S, const Ptrs& P, const Epi& E) {
;     ...
;         for (int t = 0; t < nt; t += 2) {
;             const bool last = (t == nt - 2);
;             const char* a1 = cA + (size_t)(t + 1) * kstep;
;             const char* a2 = last ? nA : cA + (size_t)(t + 2) * kstep; const char* b2 = last ? nB : cB + (size_t)(t + 2) * kstep;
;             const char* a3 = a2 + kstep; const char* b3 = b2 + kstep;
;             PG8_LDB(B0, 0, 0); PG8_SCHED; PG8_LDA(At, 0, 0); PG8_STAGE(PG8_SA(1, 1), a1 + hstep, voffA);
;             PG8_WAIT_L(8); PG8_BAR; PG8_WAIT_L(0); PG8_MMA(0, 0, At, B0); PG8_BAR; PG8_SCHED;
;             PG8_LDB(B1, 0, 1); PG8_STAGE(PG8_SB(0, 0), b2, voffB);
;             PG8_BAR; PG8_WAIT_L(0); PG8_MMA(0, 1, At, B1); PG8_BAR;
;             PG8_LDA(At, 0, 1); PG8_STAGE(PG8_SA(0, 0), a2, voffA);
;             PG8_BAR; PG8_WAIT_L(0); PG8_MMA(1, 0, At, B0); PG8_BAR; PG8_SCHED;
;             PG8_STAGE(PG8_SB(0, 1), b2 + hstep, voffB);
.LBB0_433:
	ds_read_b128 v[152:155], v149
	ds_read_b128 v[156:159], v149 offset:1024
	ds_read_b128 v[160:163], v149 offset:2048
	ds_read_b128 v[164:167], v149 offset:3072
	s_add_u32 s42, s40, 0xfffc0080
	s_addc_u32 s43, s41, -1
	s_cmp_eq_u32 s70, 12
	s_cselect_b32 s45, s1, s43
	s_cselect_b32 s44, s0, s42
	s_cselect_b32 s43, s37, s25
	s_cselect_b32 s42, s36, s23
	s_add_i32 m0, s39, 0xc000
	ds_read_b128 v[168:171], v150
	ds_read_b128 v[172:175], v150 offset:1024
	ds_read_b128 v[176:179], v150 offset:2048
	ds_read_b128 v[180:183], v150 offset:3072
	ds_read_b128 v[184:187], v150 offset:4096
	ds_read_b128 v[188:191], v150 offset:5120
	ds_read_b128 v[192:195], v150 offset:6144
	ds_read_b128 v[196:199], v150 offset:7168
	global_load_lds_dwordx4 v136, s[40:41]
	s_add_i32 m0, s39, 0xe000
	s_nop 0
	global_load_lds_dwordx4 v138, s[40:41]
	s_waitcnt lgkmcnt(8)
	s_barrier
	s_waitcnt lgkmcnt(0)
	s_setprio 1
	s_waitcnt lgkmcnt(0)
	v_mfma_f32_16x16x32_bf16 v[124:127], v[152:155], v[168:171], v[124:127]
	v_mfma_f32_16x16x32_bf16 v[124:127], v[156:159], v[172:175], v[124:127]
	v_mfma_f32_16x16x32_bf16 v[120:123], v[164:167], v[172:175], v[120:123]
	v_mfma_f32_16x16x32_bf16 v[120:123], v[160:163], v[168:171], v[120:123]
	v_mfma_f32_16x16x32_bf16 v[104:107], v[160:163], v[176:179], v[104:107]
	v_mfma_f32_16x16x32_bf16 v[104:107], v[164:167], v[180:183], v[104:107]
	v_mfma_f32_16x16x32_bf16 v[108:111], v[156:159], v[180:183], v[108:111]
	v_mfma_f32_16x16x32_bf16 v[108:111], v[152:155], v[176:179], v[108:111]
	v_mfma_f32_16x16x32_bf16 v[92:95], v[152:155], v[184:187], v[92:95]
	v_mfma_f32_16x16x32_bf16 v[92:95], v[156:159], v[188:191], v[92:95]
	v_mfma_f32_16x16x32_bf16 v[88:91], v[164:167], v[188:191], v[88:91]
	v_mfma_f32_16x16x32_bf16 v[88:91], v[160:163], v[184:187], v[88:91]
	v_mfma_f32_16x16x32_bf16 v[72:75], v[160:163], v[192:195], v[72:75]
	v_mfma_f32_16x16x32_bf16 v[72:75], v[164:167], v[196:199], v[72:75]
	v_mfma_f32_16x16x32_bf16 v[76:79], v[156:159], v[196:199], v[76:79]
	v_mfma_f32_16x16x32_bf16 v[76:79], v[152:155], v[192:195], v[76:79]
	s_setprio 0
	s_barrier
	s_add_i32 s71, s63, s51
	v_lshl_add_u64 v[144:145], s[42:43], 0, v[130:131]
	s_mov_b32 m0, s71
	ds_read_b128 v[200:203], v151
	ds_read_b128 v[204:207], v151 offset:1024
	ds_read_b128 v[210:213], v151 offset:2048
	ds_read_b128 v[214:217], v151 offset:3072
	global_load_lds_dwordx4 v[144:145], off
	v_lshl_add_u64 v[218:219], s[42:43], 0, v[134:135]
	s_add_i32 m0, s71, 0x2000
	s_nop 0
	global_load_lds_dwordx4 v[218:219], off
	s_barrier
	s_waitcnt lgkmcnt(0)
	s_setprio 1
	s_waitcnt lgkmcnt(0)
	v_mfma_f32_16x16x32_bf16 v[116:119], v[200:203], v[168:171], v[116:119]
	v_mfma_f32_16x16x32_bf16 v[116:119], v[204:207], v[172:175], v[116:119]
	v_mfma_f32_16x16x32_bf16 v[112:115], v[214:217], v[172:175], v[112:115]
	v_mfma_f32_16x16x32_bf16 v[112:115], v[210:213], v[168:171], v[112:115]
	v_mfma_f32_16x16x32_bf16 v[96:99], v[210:213], v[176:179], v[96:99]
	v_mfma_f32_16x16x32_bf16 v[96:99], v[214:217], v[180:183], v[96:99]
	v_mfma_f32_16x16x32_bf16 v[100:103], v[204:207], v[180:183], v[100:103]
	v_mfma_f32_16x16x32_bf16 v[100:103], v[200:203], v[176:179], v[100:103]
	v_mfma_f32_16x16x32_bf16 v[84:87], v[200:203], v[184:187], v[84:87]
	v_mfma_f32_16x16x32_bf16 v[84:87], v[204:207], v[188:191], v[84:87]
	v_mfma_f32_16x16x32_bf16 v[80:83], v[214:217], v[188:191], v[80:83]
	v_mfma_f32_16x16x32_bf16 v[80:83], v[210:213], v[184:187], v[80:83]
	v_mfma_f32_16x16x32_bf16 v[64:67], v[210:213], v[192:195], v[64:67]
	v_mfma_f32_16x16x32_bf16 v[64:67], v[214:217], v[196:199], v[64:67]
	v_mfma_f32_16x16x32_bf16 v[68:71], v[204:207], v[196:199], v[68:71]
	v_mfma_f32_16x16x32_bf16 v[68:71], v[200:203], v[192:195], v[68:71]
	s_setprio 0
	s_mov_b32 m0, s39
	v_lshl_add_u64 v[220:221], s[44:45], 0, v[128:129]
	s_barrier
	ds_read_b128 v[168:171], v150 offset:16384
	ds_read_b128 v[172:175], v150 offset:17408
	ds_read_b128 v[176:179], v150 offset:18432
	ds_read_b128 v[180:183], v150 offset:19456
	ds_read_b128 v[184:187], v150 offset:20480
	ds_read_b128 v[188:191], v150 offset:21504
	ds_read_b128 v[192:195], v150 offset:22528
	ds_read_b128 v[196:199], v150 offset:23552
	global_load_lds_dwordx4 v[220:221], off
	v_lshl_add_u64 v[222:223], s[44:45], 0, v[132:133]
	s_mov_b32 m0, s56
	s_nop 0
	global_load_lds_dwordx4 v[222:223], off
	s_barrier
	s_waitcnt lgkmcnt(0)
	s_setprio 1
	s_waitcnt lgkmcnt(0)
	v_mfma_f32_16x16x32_bf16 v[60:63], v[152:155], v[168:171], v[60:63]
	v_mfma_f32_16x16x32_bf16 v[60:63], v[156:159], v[172:175], v[60:63]
	v_mfma_f32_16x16x32_bf16 v[56:59], v[164:167], v[172:175], v[56:59]
	v_mfma_f32_16x16x32_bf16 v[56:59], v[160:163], v[168:171], v[56:59]
	v_mfma_f32_16x16x32_bf16 v[40:43], v[160:163], v[176:179], v[40:43]
	v_mfma_f32_16x16x32_bf16 v[40:43], v[164:167], v[180:183], v[40:43]
	v_mfma_f32_16x16x32_bf16 v[44:47], v[156:159], v[180:183], v[44:47]
	v_mfma_f32_16x16x32_bf16 v[44:47], v[152:155], v[176:179], v[44:47]
	v_mfma_f32_16x16x32_bf16 v[28:31], v[152:155], v[184:187], v[28:31]
	v_mfma_f32_16x16x32_bf16 v[28:31], v[156:159], v[188:191], v[28:31]
	v_mfma_f32_16x16x32_bf16 v[24:27], v[164:167], v[188:191], v[24:27]
	v_mfma_f32_16x16x32_bf16 v[24:27], v[160:163], v[184:187], v[24:27]
	v_mfma_f32_16x16x32_bf16 v[8:11], v[160:163], v[192:195], v[8:11]
	v_mfma_f32_16x16x32_bf16 v[8:11], v[164:167], v[196:199], v[8:11]
	v_mfma_f32_16x16x32_bf16 v[12:15], v[156:159], v[196:199], v[12:15]
	v_mfma_f32_16x16x32_bf16 v[12:15], v[152:155], v[192:195], v[12:15]
	s_setprio 0
	s_barrier
	s_add_u32 s72, s42, 0x40000
	s_addc_u32 s73, s43, 0
	s_add_i32 s71, s64, s51
	s_mov_b32 m0, s71
	s_nop 0
	global_load_lds_dwordx4 v130, s[72:73]
	s_add_i32 m0, s71, 0x2000
	s_nop 0
	global_load_lds_dwordx4 v134, s[72:73]
	s_waitcnt vmcnt(6)
	s_barrier
; #define PG8_STAGE(bufoff, gbase, voff) do { _Pragma("unroll") for (int _i = 0; _i < 2; ++_i) \
;         __builtin_amdgcn_global_load_lds((const unsigned*)((const char*)(gbase) + (voff)[_i]), (LAS unsigned*)(lds + (bufoff) + ldsw + _i * 8192), 16, 0, 0); } while (0)
; #define PG8_LDA(dst, b, h) do { _Pragma("unroll") for (int m = 0; m < 4; ++m) _Pragma("unroll") for (int k = 0; k < 2; ++k) dst[m][k] = *(const LAS bf16x8*)(lds + PG8_SA(b, h) + aoff + m * 2048 + k * 1024); } while (0)
; #define PG8_LDB(dst, b, h) do { _Pragma("unroll") for (int n = 0; n < 2; ++n) _Pragma("unroll") for (int k = 0; k < 2; ++k) dst[n][k] = *(const LAS bf16x8*)(lds + PG8_SB(b, h) + boff + n * 2048 + k * 1024); } while (0)
; #define PG8_MMA(ai, bj, At, Bt) do { __builtin_amdgcn_s_setprio(1); _Pragma("unroll") for (int m = 0; m < 4; ++m) _Pragma("unroll") for (int n = 0; n < 2; ++n) _Pragma("unroll") for (int k = 0; k < 2; ++k) \
;         acc[ai][bj][m][n] = __builtin_amdgcn_mfma_f32_16x16x32_bf16(Bt[n][k], At[m][k], acc[ai][bj][m][n], 0, 0, 0); __builtin_amdgcn_s_setprio(0); } while (0)
; #define PG8_WAIT_V(n) asm volatile("s_waitcnt vmcnt(" #n ")" ::: "memory")
; #define PG8_WAIT_L(n) asm volatile("s_waitcnt lgkmcnt(" #n ")" ::: "memory")
; #define PG8_BAR __builtin_amdgcn_s_barrier()
; #define PG8_SCHED __builtin_amdgcn_sched_barrier(0)
; template <class Epi, class Ptrs>
; __device__ __forceinline__ void gemm_phase(LAS unsigned char* lds, const int K, const StaticOrder& S, const Ptrs& P, const Epi& E) {
;     ...
;             PG8_WAIT_V(6); PG8_BAR; PG8_MMA(1, 1, At, B1); PG8_BAR;
;             PG8_LDB(B0, 1, 0); PG8_SCHED; PG8_LDA(At, 1, 0); PG8_STAGE(PG8_SA(0, 1), a2 + hstep, voffA);
;             PG8_WAIT_L(8); PG8_BAR; PG8_WAIT_L(0); PG8_MMA(0, 0, At, B0); PG8_BAR; PG8_SCHED;
;             PG8_LDB(B1, 1, 1); PG8_STAGE(PG8_SB(1, 0), b3, voffB);
;             PG8_BAR; PG8_WAIT_L(0); PG8_MMA(0, 1, At, B1); PG8_BAR;
;             PG8_LDA(At, 1, 1); PG8_STAGE(PG8_SA(1, 0), a3, voffA);
	s_setprio 1
	v_mfma_f32_16x16x32_bf16 v[52:55], v[200:203], v[168:171], v[52:55]
	v_mfma_f32_16x16x32_bf16 v[52:55], v[204:207], v[172:175], v[52:55]
	v_mfma_f32_16x16x32_bf16 v[48:51], v[214:217], v[172:175], v[48:51]
	v_mfma_f32_16x16x32_bf16 v[48:51], v[210:213], v[168:171], v[48:51]
	v_mfma_f32_16x16x32_bf16 v[32:35], v[210:213], v[176:179], v[32:35]
	v_mfma_f32_16x16x32_bf16 v[32:35], v[214:217], v[180:183], v[32:35]
	v_mfma_f32_16x16x32_bf16 v[36:39], v[204:207], v[180:183], v[36:39]
	v_mfma_f32_16x16x32_bf16 v[36:39], v[200:203], v[176:179], v[36:39]
	v_mfma_f32_16x16x32_bf16 v[20:23], v[200:203], v[184:187], v[20:23]
	v_mfma_f32_16x16x32_bf16 v[20:23], v[204:207], v[188:191], v[20:23]
	v_mfma_f32_16x16x32_bf16 v[16:19], v[214:217], v[188:191], v[16:19]
	v_mfma_f32_16x16x32_bf16 v[16:19], v[210:213], v[184:187], v[16:19]
	v_mfma_f32_16x16x32_bf16 v[0:3], v[210:213], v[192:195], v[0:3]
	v_mfma_f32_16x16x32_bf16 v[0:3], v[214:217], v[196:199], v[0:3]
	v_mfma_f32_16x16x32_bf16 v[4:7], v[204:207], v[196:199], v[4:7]
	v_mfma_f32_16x16x32_bf16 v[4:7], v[200:203], v[192:195], v[4:7]
	s_setprio 0
	s_add_i32 s71, 0, 0x18000
	v_add_u32_e32 v164, s71, v147
	s_barrier
	ds_read_b128 v[152:155], v164
	ds_read_b128 v[156:159], v164 offset:1024
	ds_read_b128 v[160:163], v164 offset:2048
	ds_read_b128 v[164:167], v164 offset:3072
	s_add_u32 s44, s44, 0x40000
	s_addc_u32 s45, s45, 0
	s_mov_b32 m0, s57
	ds_read_b128 v[168:171], v150 offset:32768
	ds_read_b128 v[172:175], v150 offset:33792
	ds_read_b128 v[176:179], v150 offset:34816
	ds_read_b128 v[180:183], v150 offset:35840
	ds_read_b128 v[184:187], v150 offset:36864
	ds_read_b128 v[188:191], v150 offset:37888
	ds_read_b128 v[192:195], v150 offset:38912
	ds_read_b128 v[196:199], v150 offset:39936
	global_load_lds_dwordx4 v128, s[44:45]
	s_mov_b32 m0, s58
	s_nop 0
	global_load_lds_dwordx4 v132, s[44:45]
	s_waitcnt lgkmcnt(8)
	s_barrier
	s_waitcnt lgkmcnt(0)
	s_setprio 1
	s_waitcnt lgkmcnt(0)
	v_mfma_f32_16x16x32_bf16 v[124:127], v[152:155], v[168:171], v[124:127]
	v_mfma_f32_16x16x32_bf16 v[124:127], v[156:159], v[172:175], v[124:127]
	v_mfma_f32_16x16x32_bf16 v[120:123], v[164:167], v[172:175], v[120:123]
	v_mfma_f32_16x16x32_bf16 v[120:123], v[160:163], v[168:171], v[120:123]
	v_mfma_f32_16x16x32_bf16 v[104:107], v[160:163], v[176:179], v[104:107]
	v_mfma_f32_16x16x32_bf16 v[104:107], v[164:167], v[180:183], v[104:107]
	v_mfma_f32_16x16x32_bf16 v[108:111], v[156:159], v[180:183], v[108:111]
	v_mfma_f32_16x16x32_bf16 v[108:111], v[152:155], v[176:179], v[108:111]
	v_mfma_f32_16x16x32_bf16 v[92:95], v[152:155], v[184:187], v[92:95]
	v_mfma_f32_16x16x32_bf16 v[92:95], v[156:159], v[188:191], v[92:95]
	v_mfma_f32_16x16x32_bf16 v[88:91], v[164:167], v[188:191], v[88:91]
	v_mfma_f32_16x16x32_bf16 v[88:91], v[160:163], v[184:187], v[88:91]
	v_mfma_f32_16x16x32_bf16 v[72:75], v[160:163], v[192:195], v[72:75]
	v_mfma_f32_16x16x32_bf16 v[72:75], v[164:167], v[196:199], v[72:75]
	v_mfma_f32_16x16x32_bf16 v[76:79], v[156:159], v[196:199], v[76:79]
	v_mfma_f32_16x16x32_bf16 v[76:79], v[152:155], v[192:195], v[76:79]
	s_setprio 0
	s_barrier
	s_add_i32 s44, 0, 0x1c000
	s_add_i32 s45, s71, s51
	v_add_u32_e32 v209, s44, v147
	v_lshl_add_u64 v[144:145], v[144:145], 0, s[12:13]
	s_mov_b32 m0, s45
	ds_read_b128 v[200:203], v209
	ds_read_b128 v[204:207], v209 offset:1024
	ds_read_b128 v[210:213], v209 offset:2048
	ds_read_b128 v[214:217], v209 offset:3072
	global_load_lds_dwordx4 v[144:145], off
	v_lshl_add_u64 v[144:145], v[218:219], 0, s[12:13]
	s_add_i32 m0, s45, 0x2000
	s_nop 0
	global_load_lds_dwordx4 v[144:145], off
	s_barrier
	s_waitcnt lgkmcnt(0)
	s_setprio 1
	s_waitcnt lgkmcnt(0)
	v_mfma_f32_16x16x32_bf16 v[116:119], v[200:203], v[168:171], v[116:119]
	v_mfma_f32_16x16x32_bf16 v[116:119], v[204:207], v[172:175], v[116:119]
	v_mfma_f32_16x16x32_bf16 v[112:115], v[214:217], v[172:175], v[112:115]
	v_mfma_f32_16x16x32_bf16 v[112:115], v[210:213], v[168:171], v[112:115]
	v_mfma_f32_16x16x32_bf16 v[96:99], v[210:213], v[176:179], v[96:99]
	v_mfma_f32_16x16x32_bf16 v[96:99], v[214:217], v[180:183], v[96:99]
	v_mfma_f32_16x16x32_bf16 v[100:103], v[204:207], v[180:183], v[100:103]
	v_mfma_f32_16x16x32_bf16 v[100:103], v[200:203], v[176:179], v[100:103]
	v_mfma_f32_16x16x32_bf16 v[84:87], v[200:203], v[184:187], v[84:87]
	v_mfma_f32_16x16x32_bf16 v[84:87], v[204:207], v[188:191], v[84:87]
	v_mfma_f32_16x16x32_bf16 v[80:83], v[214:217], v[188:191], v[80:83]
	v_mfma_f32_16x16x32_bf16 v[80:83], v[210:213], v[184:187], v[80:83]
	v_mfma_f32_16x16x32_bf16 v[64:67], v[210:213], v[192:195], v[64:67]
	v_mfma_f32_16x16x32_bf16 v[64:67], v[214:217], v[196:199], v[64:67]
	v_mfma_f32_16x16x32_bf16 v[68:71], v[204:207], v[196:199], v[68:71]
	v_mfma_f32_16x16x32_bf16 v[68:71], v[200:203], v[192:195], v[68:71]
	s_setprio 0
	s_mov_b32 m0, s61
	v_lshl_add_u64 v[144:145], v[220:221], 0, s[12:13]
	s_barrier
	ds_read_b128 v[168:171], v150 offset:49152
	ds_read_b128 v[172:175], v150 offset:50176
	ds_read_b128 v[176:179], v150 offset:51200
	ds_read_b128 v[180:183], v150 offset:52224
	ds_read_b128 v[184:187], v150 offset:53248
	ds_read_b128 v[188:191], v150 offset:54272
	ds_read_b128 v[192:195], v150 offset:55296
	ds_read_b128 v[196:199], v150 offset:56320
	global_load_lds_dwordx4 v[144:145], off
	v_lshl_add_u64 v[144:145], v[222:223], 0, s[12:13]
	s_mov_b32 m0, s62
	s_nop 0
	global_load_lds_dwordx4 v[144:145], off
	s_barrier
; __device__ __forceinline__ unsigned cvt_pk_bf16(float lo, float hi) { unsigned r; asm volatile("v_cvt_pk_bf16_f32 %0, %1, %2" : "=v"(r) : "v"(lo), "v"(hi)); return r; }
; #define PG8_STAGE(bufoff, gbase, voff) do { _Pragma("unroll") for (int _i = 0; _i < 2; ++_i) \
;         __builtin_amdgcn_global_load_lds((const unsigned*)((const char*)(gbase) + (voff)[_i]), (LAS unsigned*)(lds + (bufoff) + ldsw + _i * 8192), 16, 0, 0); } while (0)
; #define PG8_MMA(ai, bj, At, Bt) do { __builtin_amdgcn_s_setprio(1); _Pragma("unroll") for (int m = 0; m < 4; ++m) _Pragma("unroll") for (int n = 0; n < 2; ++n) _Pragma("unroll") for (int k = 0; k < 2; ++k) \
;         acc[ai][bj][m][n] = __builtin_amdgcn_mfma_f32_16x16x32_bf16(Bt[n][k], At[m][k], acc[ai][bj][m][n], 0, 0, 0); __builtin_amdgcn_s_setprio(0); } while (0)
; #define PG8_WAIT_V(n) asm volatile("s_waitcnt vmcnt(" #n ")" ::: "memory")
; #define PG8_WAIT_L(n) asm volatile("s_waitcnt lgkmcnt(" #n ")" ::: "memory")
; #define PG8_BAR __builtin_amdgcn_s_barrier()
; #define PG8_SCHED __builtin_amdgcn_sched_barrier(0)
; template <class Epi, class Ptrs>
; __device__ __forceinline__ void gemm_phase(LAS unsigned char* lds, const int K, const StaticOrder& S, const Ptrs& P, const Epi& E) {
;     ...
;             PG8_BAR; PG8_WAIT_L(0); PG8_MMA(1, 0, At, B0); PG8_BAR; PG8_SCHED;
;             PG8_STAGE(PG8_SB(1, 1), b3 + hstep, voffB);
;             PG8_WAIT_V(6); PG8_BAR; PG8_MMA(1, 1, At, B1); PG8_BAR;
;         }
;     __device__ __forceinline__ void operator()(const f32x4 (&acc)[2][2][4][2], const Unit& u, int ui, int wr, int wc, int fr, int fq) const {
;         const int row0 = u.pm * 256 + wr * 64 + fr, col0 = u.pn * 256 + wc * 32 + 8 * fq;
; #pragma unroll
;         for (int ai = 0; ai < 2; ++ai)
; #pragma unroll
;             for (int m = 0; m < 4; ++m) { bf16_t* rowp = hid + (size_t)(row0 + ai * 128 + m * 16) * DFF + col0;
; #pragma unroll
;                 for (int bj = 0; bj < 2; ++bj) { f32x4 v0 = acc[ai][bj][m][0], v1 = acc[ai][bj][m][1];
; #pragma unroll
;                     for (int j = 0; j < 4; ++j) { const float a = fmaxf(v0[j], 0.f), b = fmaxf(v1[j], 0.f); v0[j] = a * a; v1[j] = b * b; }
;                     u32x4 w; w.x = cvt_pk_bf16(v0[0], v0[1]); w.y = cvt_pk_bf16(v0[2], v0[3]); w.z = cvt_pk_bf16(v1[0], v1[1]); w.w = cvt_pk_bf16(v1[2], v1[3]);
;                     *(u32x4*)(rowp + bj * 128) = w; } }
	s_waitcnt lgkmcnt(0)
	s_setprio 1
	s_waitcnt lgkmcnt(0)
	v_mfma_f32_16x16x32_bf16 v[60:63], v[152:155], v[168:171], v[60:63]
	v_mfma_f32_16x16x32_bf16 v[60:63], v[156:159], v[172:175], v[60:63]
	v_mfma_f32_16x16x32_bf16 v[56:59], v[164:167], v[172:175], v[56:59]
	v_mfma_f32_16x16x32_bf16 v[56:59], v[160:163], v[168:171], v[56:59]
	v_mfma_f32_16x16x32_bf16 v[40:43], v[160:163], v[176:179], v[40:43]
	v_mfma_f32_16x16x32_bf16 v[40:43], v[164:167], v[180:183], v[40:43]
	v_mfma_f32_16x16x32_bf16 v[44:47], v[156:159], v[180:183], v[44:47]
	v_mfma_f32_16x16x32_bf16 v[44:47], v[152:155], v[176:179], v[44:47]
	v_mfma_f32_16x16x32_bf16 v[28:31], v[152:155], v[184:187], v[28:31]
	v_mfma_f32_16x16x32_bf16 v[28:31], v[156:159], v[188:191], v[28:31]
	v_mfma_f32_16x16x32_bf16 v[24:27], v[164:167], v[188:191], v[24:27]
	v_mfma_f32_16x16x32_bf16 v[24:27], v[160:163], v[184:187], v[24:27]
	v_mfma_f32_16x16x32_bf16 v[8:11], v[160:163], v[192:195], v[8:11]
	v_mfma_f32_16x16x32_bf16 v[8:11], v[164:167], v[196:199], v[8:11]
	v_mfma_f32_16x16x32_bf16 v[12:15], v[156:159], v[196:199], v[12:15]
	v_mfma_f32_16x16x32_bf16 v[12:15], v[152:155], v[192:195], v[12:15]
	s_setprio 0
	s_barrier
	s_add_u32 s42, s42, 0x40080
	s_addc_u32 s43, s43, 0
	s_add_i32 s44, s44, s51
	s_mov_b32 m0, s44
	s_nop 0
	global_load_lds_dwordx4 v130, s[42:43]
	s_add_i32 m0, s44, 0x2000
	s_nop 0
	global_load_lds_dwordx4 v134, s[42:43]
	s_waitcnt vmcnt(6)
	s_barrier
	s_setprio 1
	v_mfma_f32_16x16x32_bf16 v[52:55], v[200:203], v[168:171], v[52:55]
	v_mfma_f32_16x16x32_bf16 v[52:55], v[204:207], v[172:175], v[52:55]
	v_mfma_f32_16x16x32_bf16 v[48:51], v[214:217], v[172:175], v[48:51]
	v_mfma_f32_16x16x32_bf16 v[48:51], v[210:213], v[168:171], v[48:51]
	v_mfma_f32_16x16x32_bf16 v[32:35], v[210:213], v[176:179], v[32:35]
	v_mfma_f32_16x16x32_bf16 v[32:35], v[214:217], v[180:183], v[32:35]
	v_mfma_f32_16x16x32_bf16 v[36:39], v[204:207], v[180:183], v[36:39]
	v_mfma_f32_16x16x32_bf16 v[36:39], v[200:203], v[176:179], v[36:39]
	v_mfma_f32_16x16x32_bf16 v[20:23], v[200:203], v[184:187], v[20:23]
	v_mfma_f32_16x16x32_bf16 v[20:23], v[204:207], v[188:191], v[20:23]
	v_mfma_f32_16x16x32_bf16 v[16:19], v[214:217], v[188:191], v[16:19]
	v_mfma_f32_16x16x32_bf16 v[16:19], v[210:213], v[184:187], v[16:19]
	v_mfma_f32_16x16x32_bf16 v[0:3], v[210:213], v[192:195], v[0:3]
	v_mfma_f32_16x16x32_bf16 v[0:3], v[214:217], v[196:199], v[0:3]
	v_mfma_f32_16x16x32_bf16 v[4:7], v[204:207], v[196:199], v[4:7]
	v_mfma_f32_16x16x32_bf16 v[4:7], v[200:203], v[192:195], v[4:7]
	s_setprio 0
	s_add_i32 s70, s70, 2
	s_add_u32 s40, s40, 0x100
	s_addc_u32 s41, s41, 0
	s_add_u32 s23, s23, 0x100
	s_addc_u32 s25, s25, 0
	s_cmp_gt_u32 s70, 13
	s_barrier
	s_cbranch_scc0 .LBB0_433
	s_nop 0
	s_nop 0
	s_nop 0
	s_nop 0
	s_nop 0
	s_nop 0
	s_nop 0
	s_nop 0
	s_nop 0
	s_nop 0
	s_nop 0
	s_nop 0
	s_nop 0
	s_nop 0
	s_nop 0
	s_nop 0
	v_lshl_add_u32 v152, s38, 8, v146
	v_max_f32_e32 v120, 0, v120
	v_ashrrev_i32_e32 v153, 31, v152
	v_max_f32_e32 v121, 0, v121
	v_max_f32_e32 v122, 0, v122
	v_lshl_or_b32 v144, s69, 8, v148
	v_lshlrev_b64 v[154:155], 13, v[152:153]
	v_mul_f32_e32 v153, v120, v120
	v_max_f32_e32 v120, 0, v125
	v_ashrrev_i32_e32 v145, 31, v144
	v_max_f32_e32 v124, 0, v124
	v_mul_f32_e32 v125, v121, v121
	v_max_f32_e32 v121, 0, v126
	v_mul_f32_e32 v126, v122, v122
	v_max_f32_e32 v122, 0, v127
	v_max_f32_e32 v123, 0, v123
	v_lshl_add_u64 v[154:155], s[10:11], 0, v[154:155]
	v_lshlrev_b64 v[156:157], 1, v[144:145]
	v_mul_f32_e32 v120, v120, v120
	v_max_f32_e32 v112, 0, v112
	v_lshl_add_u64 v[144:145], v[154:155], 0, v[156:157]
	v_mul_f32_e32 v124, v124, v124
	v_mul_f32_e32 v121, v121, v121
	v_mul_f32_e32 v122, v122, v122
	v_mul_f32_e32 v123, v123, v123
	v_cvt_pk_bf16_f32 v120, v124, v120
	v_max_f32_e32 v113, 0, v113
	v_max_f32_e32 v114, 0, v114
	v_cvt_pk_bf16_f32 v121, v121, v122
	v_cvt_pk_bf16_f32 v122, v153, v125
	v_cvt_pk_bf16_f32 v123, v126, v123
	global_store_dwordx4 v[144:145], v[120:123], off
	s_nop 1
	v_mul_f32_e32 v120, v112, v112
	v_max_f32_e32 v112, 0, v117
	v_max_f32_e32 v116, 0, v116
	v_mul_f32_e32 v117, v113, v113
	v_max_f32_e32 v113, 0, v118
	v_mul_f32_e32 v118, v114, v114
	v_max_f32_e32 v114, 0, v119
	v_max_f32_e32 v115, 0, v115
	v_mul_f32_e32 v112, v112, v112
	v_mul_f32_e32 v116, v116, v116
	v_mul_f32_e32 v113, v113, v113
	v_mul_f32_e32 v114, v114, v114
	v_mul_f32_e32 v115, v115, v115
	v_cvt_pk_bf16_f32 v112, v116, v112
	v_max_f32_e32 v104, 0, v104
	v_cvt_pk_bf16_f32 v113, v113, v114
	v_cvt_pk_bf16_f32 v114, v120, v117
	v_cvt_pk_bf16_f32 v115, v118, v115
	global_store_dwordx4 v[144:145], v[112:115], off offset:256
	s_nop 0
	v_max_f32_e32 v105, 0, v105
	v_or_b32_e32 v112, 16, v152
	v_max_f32_e32 v106, 0, v106
	v_ashrrev_i32_e32 v113, 31, v112
	v_mul_f32_e32 v114, v104, v104
	v_max_f32_e32 v104, 0, v109
	v_lshlrev_b64 v[112:113], 13, v[112:113]
	v_max_f32_e32 v108, 0, v108
	v_mul_f32_e32 v109, v105, v105
	v_max_f32_e32 v105, 0, v110
	v_mul_f32_e32 v110, v106, v106
	v_max_f32_e32 v106, 0, v111
	v_max_f32_e32 v107, 0, v107
	v_lshl_add_u64 v[112:113], s[10:11], 0, v[112:113]
	v_mul_f32_e32 v104, v104, v104
	v_max_f32_e32 v96, 0, v96
	v_lshl_add_u64 v[112:113], v[112:113], 0, v[156:157]
	v_mul_f32_e32 v108, v108, v108
	v_mul_f32_e32 v105, v105, v105
	v_mul_f32_e32 v106, v106, v106
	v_mul_f32_e32 v107, v107, v107
	v_cvt_pk_bf16_f32 v104, v108, v104
	v_max_f32_e32 v97, 0, v97
	v_max_f32_e32 v98, 0, v98
	v_cvt_pk_bf16_f32 v105, v105, v106
	v_cvt_pk_bf16_f32 v106, v114, v109
	v_cvt_pk_bf16_f32 v107, v110, v107
	global_store_dwordx4 v[112:113], v[104:107], off
	s_nop 1
	v_mul_f32_e32 v104, v96, v96
	v_max_f32_e32 v96, 0, v101
; __device__ __forceinline__ unsigned cvt_pk_bf16(float lo, float hi) { unsigned r; asm volatile("v_cvt_pk_bf16_f32 %0, %1, %2" : "=v"(r) : "v"(lo), "v"(hi)); return r; }
;     __device__ __forceinline__ void operator()(const f32x4 (&acc)[2][2][4][2], const Unit& u, int ui, int wr, int wc, int fr, int fq) const {
;     ...
;         for (int ai = 0; ai < 2; ++ai)
; #pragma unroll
;             for (int m = 0; m < 4; ++m) { bf16_t* rowp = hid + (size_t)(row0 + ai * 128 + m * 16) * DFF + col0;
; #pragma unroll
;                 for (int bj = 0; bj < 2; ++bj) { f32x4 v0 = acc[ai][bj][m][0], v1 = acc[ai][bj][m][1];
; #pragma unroll
;                     for (int j = 0; j < 4; ++j) { const float a = fmaxf(v0[j], 0.f), b = fmaxf(v1[j], 0.f); v0[j] = a * a; v1[j] = b * b; }
;                     u32x4 w; w.x = cvt_pk_bf16(v0[0], v0[1]); w.y = cvt_pk_bf16(v0[2], v0[3]); w.z = cvt_pk_bf16(v1[0], v1[1]); w.w = cvt_pk_bf16(v1[2], v1[3]);
;                     *(u32x4*)(rowp + bj * 128) = w; } }
	v_max_f32_e32 v100, 0, v100
	v_mul_f32_e32 v101, v97, v97
	v_max_f32_e32 v97, 0, v102
	v_mul_f32_e32 v102, v98, v98
	v_max_f32_e32 v98, 0, v103
	v_max_f32_e32 v99, 0, v99
	v_mul_f32_e32 v96, v96, v96
	v_mul_f32_e32 v100, v100, v100
	v_mul_f32_e32 v97, v97, v97
	v_mul_f32_e32 v98, v98, v98
	v_mul_f32_e32 v99, v99, v99
	v_cvt_pk_bf16_f32 v96, v100, v96
	v_max_f32_e32 v88, 0, v88
	v_cvt_pk_bf16_f32 v97, v97, v98
	v_cvt_pk_bf16_f32 v98, v104, v101
	v_cvt_pk_bf16_f32 v99, v102, v99
	global_store_dwordx4 v[112:113], v[96:99], off offset:256
	s_nop 0
	v_max_f32_e32 v89, 0, v89
	v_or_b32_e32 v96, 32, v152
	v_max_f32_e32 v90, 0, v90
	v_ashrrev_i32_e32 v97, 31, v96
	v_mul_f32_e32 v98, v88, v88
	v_max_f32_e32 v88, 0, v93
	v_lshlrev_b64 v[96:97], 13, v[96:97]
	v_max_f32_e32 v92, 0, v92
	v_mul_f32_e32 v93, v89, v89
	v_max_f32_e32 v89, 0, v94
	v_mul_f32_e32 v94, v90, v90
	v_max_f32_e32 v90, 0, v95
	v_max_f32_e32 v91, 0, v91
	v_lshl_add_u64 v[96:97], s[10:11], 0, v[96:97]
	v_mul_f32_e32 v88, v88, v88
	v_max_f32_e32 v80, 0, v80
	v_lshl_add_u64 v[96:97], v[96:97], 0, v[156:157]
	v_mul_f32_e32 v92, v92, v92
	v_mul_f32_e32 v89, v89, v89
	v_mul_f32_e32 v90, v90, v90
	v_mul_f32_e32 v91, v91, v91
	v_cvt_pk_bf16_f32 v88, v92, v88
	v_max_f32_e32 v81, 0, v81
	v_max_f32_e32 v82, 0, v82
	v_cvt_pk_bf16_f32 v89, v89, v90
	v_cvt_pk_bf16_f32 v90, v98, v93
	v_cvt_pk_bf16_f32 v91, v94, v91
	global_store_dwordx4 v[96:97], v[88:91], off
	s_nop 1
	v_mul_f32_e32 v88, v80, v80
	v_max_f32_e32 v80, 0, v85
	v_max_f32_e32 v84, 0, v84
	v_mul_f32_e32 v85, v81, v81
	v_max_f32_e32 v81, 0, v86
	v_mul_f32_e32 v86, v82, v82
	v_max_f32_e32 v82, 0, v87
	v_max_f32_e32 v83, 0, v83
	v_mul_f32_e32 v80, v80, v80
	v_mul_f32_e32 v84, v84, v84
	v_mul_f32_e32 v81, v81, v81
	v_mul_f32_e32 v82, v82, v82
	v_mul_f32_e32 v83, v83, v83
	v_cvt_pk_bf16_f32 v80, v84, v80
	v_max_f32_e32 v72, 0, v72
	v_cvt_pk_bf16_f32 v81, v81, v82
	v_cvt_pk_bf16_f32 v82, v88, v85
	v_cvt_pk_bf16_f32 v83, v86, v83
	global_store_dwordx4 v[96:97], v[80:83], off offset:256
	s_nop 0
	v_max_f32_e32 v73, 0, v73
	v_or_b32_e32 v80, 48, v152
	v_max_f32_e32 v74, 0, v74
	v_ashrrev_i32_e32 v81, 31, v80
	v_mul_f32_e32 v82, v72, v72
	v_max_f32_e32 v72, 0, v77
	v_lshlrev_b64 v[80:81], 13, v[80:81]
	v_max_f32_e32 v76, 0, v76
	v_mul_f32_e32 v77, v73, v73
	v_max_f32_e32 v73, 0, v78
	v_mul_f32_e32 v78, v74, v74
	v_max_f32_e32 v74, 0, v79
	v_max_f32_e32 v75, 0, v75
	v_lshl_add_u64 v[80:81], s[10:11], 0, v[80:81]
	v_mul_f32_e32 v72, v72, v72
	v_max_f32_e32 v64, 0, v64
	v_max_f32_e32 v65, 0, v65
	v_max_f32_e32 v66, 0, v66
	v_lshl_add_u64 v[80:81], v[80:81], 0, v[156:157]
	v_mul_f32_e32 v76, v76, v76
	v_mul_f32_e32 v73, v73, v73
	v_mul_f32_e32 v74, v74, v74
	v_mul_f32_e32 v75, v75, v75
	v_cvt_pk_bf16_f32 v72, v76, v72
	v_cvt_pk_bf16_f32 v73, v73, v74
	v_cvt_pk_bf16_f32 v74, v82, v77
	v_cvt_pk_bf16_f32 v75, v78, v75
	global_store_dwordx4 v[80:81], v[72:75], off
	v_max_f32_e32 v68, 0, v68
	v_max_f32_e32 v67, 0, v67
	v_mul_f32_e32 v72, v64, v64
	v_max_f32_e32 v64, 0, v69
	v_mul_f32_e32 v69, v65, v65
	v_max_f32_e32 v65, 0, v70
	v_mul_f32_e32 v70, v66, v66
	v_max_f32_e32 v66, 0, v71
	v_mul_f32_e32 v64, v64, v64
	v_mul_f32_e32 v65, v65, v65
	v_mul_f32_e32 v66, v66, v66
	v_max_f32_e32 v56, 0, v56
	v_mul_f32_e32 v68, v68, v68
	v_mul_f32_e32 v67, v67, v67
	v_cvt_pk_bf16_f32 v64, v68, v64
	v_cvt_pk_bf16_f32 v65, v65, v66
	v_cvt_pk_bf16_f32 v66, v72, v69
	v_max_f32_e32 v57, 0, v57
	v_max_f32_e32 v58, 0, v58
	v_cvt_pk_bf16_f32 v67, v70, v67
	global_store_dwordx4 v[80:81], v[64:67], off offset:256
	s_nop 0
	v_max_f32_e32 v60, 0, v60
	v_mul_f32_e32 v66, v56, v56
	v_max_f32_e32 v56, 0, v61
	v_mul_f32_e32 v61, v57, v57
	v_max_f32_e32 v57, 0, v62
	v_mul_f32_e32 v62, v58, v58
	v_max_f32_e32 v58, 0, v63
	v_mul_f32_e32 v60, v60, v60
	v_mul_f32_e32 v56, v56, v56
	v_max_f32_e32 v59, 0, v59
	v_mul_f32_e32 v57, v57, v57
	v_mul_f32_e32 v58, v58, v58
	v_cvt_pk_bf16_f32 v56, v60, v56
	v_add_co_u32_e32 v60, vcc, s65, v144
	v_max_f32_e32 v48, 0, v48
	v_max_f32_e32 v49, 0, v49
	v_max_f32_e32 v50, 0, v50
	v_mul_f32_e32 v59, v59, v59
	v_cvt_pk_bf16_f32 v57, v57, v58
	v_cvt_pk_bf16_f32 v58, v66, v61
	v_addc_co_u32_e32 v61, vcc, 0, v145, vcc
	v_cvt_pk_bf16_f32 v59, v62, v59
	global_store_dwordx4 v[60:61], v[56:59], off
	v_max_f32_e32 v52, 0, v52
	v_max_f32_e32 v51, 0, v51
	v_mul_f32_e32 v56, v48, v48
	v_max_f32_e32 v48, 0, v53
	v_mul_f32_e32 v53, v49, v49
	v_max_f32_e32 v49, 0, v54
	v_mul_f32_e32 v54, v50, v50
	v_max_f32_e32 v50, 0, v55
	v_mul_f32_e32 v48, v48, v48
	v_mul_f32_e32 v49, v49, v49
	v_mul_f32_e32 v50, v50, v50
	v_max_f32_e32 v40, 0, v40
; __device__ __forceinline__ unsigned cvt_pk_bf16(float lo, float hi) { unsigned r; asm volatile("v_cvt_pk_bf16_f32 %0, %1, %2" : "=v"(r) : "v"(lo), "v"(hi)); return r; }
; #define PG8_WAIT_V(n) asm volatile("s_waitcnt vmcnt(" #n ")" ::: "memory")
; #define PG8_BAR __builtin_amdgcn_s_barrier()
; template <class Epi, class Ptrs>
; __device__ __forceinline__ void gemm_phase(LAS unsigned char* lds, const int K, const StaticOrder& S, const Ptrs& P, const Epi& E) {
;     ...
;         if (!has_next) break;
; #pragma unroll
;         for (int a = 0; a < 2; ++a)
; #pragma unroll
;             for (int b = 0; b < 2; ++b)
; #pragma unroll
;                 for (int m = 0; m < 4; ++m)
; #pragma unroll
;                     for (int n = 0; n < 2; ++n) acc[a][b][m][n] = (f32x4){0.f, 0.f, 0.f, 0.f};
;         cur = nxt; cA = nA; cB = nB; ++ui;
;     }
;     PG8_WAIT_V(0);
;     if (wr == 0) PG8_BAR;
;     PG8_BAR;
;     __device__ __forceinline__ void operator()(const f32x4 (&acc)[2][2][4][2], const Unit& u, int ui, int wr, int wc, int fr, int fq) const {
;         const int row0 = u.pm * 256 + wr * 64 + fr, col0 = u.pn * 256 + wc * 32 + 8 * fq;
; #pragma unroll
;         for (int ai = 0; ai < 2; ++ai)
; #pragma unroll
;             for (int m = 0; m < 4; ++m) { bf16_t* rowp = hid + (size_t)(row0 + ai * 128 + m * 16) * DFF + col0;
; #pragma unroll
;                 for (int bj = 0; bj < 2; ++bj) { f32x4 v0 = acc[ai][bj][m][0], v1 = acc[ai][bj][m][1];
; #pragma unroll
;                     for (int j = 0; j < 4; ++j) { const float a = fmaxf(v0[j], 0.f), b = fmaxf(v1[j], 0.f); v0[j] = a * a; v1[j] = b * b; }
;                     u32x4 w; w.x = cvt_pk_bf16(v0[0], v0[1]); w.y = cvt_pk_bf16(v0[2], v0[3]); w.z = cvt_pk_bf16(v1[0], v1[1]); w.w = cvt_pk_bf16(v1[2], v1[3]);
;                     *(u32x4*)(rowp + bj * 128) = w; } }
	v_lshl_add_u64 v[64:65], v[144:145], 0, s[14:15]
	v_mul_f32_e32 v52, v52, v52
	v_mul_f32_e32 v51, v51, v51
	v_cvt_pk_bf16_f32 v48, v52, v48
	v_cvt_pk_bf16_f32 v49, v49, v50
	v_cvt_pk_bf16_f32 v50, v56, v53
	v_max_f32_e32 v41, 0, v41
	v_max_f32_e32 v42, 0, v42
	v_cvt_pk_bf16_f32 v51, v54, v51
	global_store_dwordx4 v[64:65], v[48:51], off offset:256
	s_nop 0
	v_max_f32_e32 v44, 0, v44
	v_mul_f32_e32 v50, v40, v40
	v_max_f32_e32 v40, 0, v45
	v_mul_f32_e32 v45, v41, v41
	v_max_f32_e32 v41, 0, v46
	v_mul_f32_e32 v46, v42, v42
	v_max_f32_e32 v42, 0, v47
	v_mul_f32_e32 v44, v44, v44
	v_mul_f32_e32 v40, v40, v40
	v_max_f32_e32 v43, 0, v43
	v_mul_f32_e32 v41, v41, v41
	v_mul_f32_e32 v42, v42, v42
	v_cvt_pk_bf16_f32 v40, v44, v40
	v_add_co_u32_e32 v44, vcc, s66, v144
	v_max_f32_e32 v32, 0, v32
	v_max_f32_e32 v33, 0, v33
	v_max_f32_e32 v34, 0, v34
	v_mul_f32_e32 v43, v43, v43
	v_cvt_pk_bf16_f32 v41, v41, v42
	v_cvt_pk_bf16_f32 v42, v50, v45
	v_addc_co_u32_e32 v45, vcc, 0, v145, vcc
	v_cvt_pk_bf16_f32 v43, v46, v43
	global_store_dwordx4 v[44:45], v[40:43], off
	v_max_f32_e32 v36, 0, v36
	v_max_f32_e32 v35, 0, v35
	v_mul_f32_e32 v40, v32, v32
	v_max_f32_e32 v32, 0, v37
	v_mul_f32_e32 v37, v33, v33
	v_max_f32_e32 v33, 0, v38
	v_mul_f32_e32 v38, v34, v34
	v_max_f32_e32 v34, 0, v39
	v_mul_f32_e32 v32, v32, v32
	v_mul_f32_e32 v33, v33, v33
	v_mul_f32_e32 v34, v34, v34
	v_max_f32_e32 v24, 0, v24
	v_lshl_add_u64 v[48:49], v[144:145], 0, s[16:17]
	v_mul_f32_e32 v36, v36, v36
	v_mul_f32_e32 v35, v35, v35
	v_cvt_pk_bf16_f32 v32, v36, v32
	v_cvt_pk_bf16_f32 v33, v33, v34
	v_cvt_pk_bf16_f32 v34, v40, v37
	v_max_f32_e32 v25, 0, v25
	v_max_f32_e32 v26, 0, v26
	v_cvt_pk_bf16_f32 v35, v38, v35
	global_store_dwordx4 v[48:49], v[32:35], off offset:256
	s_nop 0
	v_max_f32_e32 v28, 0, v28
	v_mul_f32_e32 v34, v24, v24
	v_max_f32_e32 v24, 0, v29
	v_mul_f32_e32 v29, v25, v25
	v_max_f32_e32 v25, 0, v30
	v_mul_f32_e32 v30, v26, v26
	v_max_f32_e32 v26, 0, v31
	v_mul_f32_e32 v28, v28, v28
	v_mul_f32_e32 v24, v24, v24
	v_max_f32_e32 v27, 0, v27
	v_mul_f32_e32 v25, v25, v25
	v_mul_f32_e32 v26, v26, v26
	v_cvt_pk_bf16_f32 v24, v28, v24
	v_add_co_u32_e32 v28, vcc, s67, v144
	v_max_f32_e32 v16, 0, v16
	v_max_f32_e32 v17, 0, v17
	v_max_f32_e32 v18, 0, v18
	v_mul_f32_e32 v27, v27, v27
	v_cvt_pk_bf16_f32 v25, v25, v26
	v_cvt_pk_bf16_f32 v26, v34, v29
	v_addc_co_u32_e32 v29, vcc, 0, v145, vcc
	v_cvt_pk_bf16_f32 v27, v30, v27
	global_store_dwordx4 v[28:29], v[24:27], off
	v_max_f32_e32 v20, 0, v20
	v_max_f32_e32 v19, 0, v19
	v_mul_f32_e32 v24, v16, v16
	v_max_f32_e32 v16, 0, v21
	v_mul_f32_e32 v21, v17, v17
	v_max_f32_e32 v17, 0, v22
	v_mul_f32_e32 v22, v18, v18
	v_max_f32_e32 v18, 0, v23
	v_mul_f32_e32 v16, v16, v16
	v_mul_f32_e32 v17, v17, v17
	v_mul_f32_e32 v18, v18, v18
	v_max_f32_e32 v8, 0, v8
	v_lshl_add_u64 v[32:33], v[144:145], 0, s[18:19]
	v_mul_f32_e32 v20, v20, v20
	v_mul_f32_e32 v19, v19, v19
	v_cvt_pk_bf16_f32 v16, v20, v16
	v_cvt_pk_bf16_f32 v17, v17, v18
	v_cvt_pk_bf16_f32 v18, v24, v21
	v_max_f32_e32 v9, 0, v9
	v_max_f32_e32 v10, 0, v10
	v_cvt_pk_bf16_f32 v19, v22, v19
	global_store_dwordx4 v[32:33], v[16:19], off offset:256
	s_nop 0
	v_max_f32_e32 v12, 0, v12
	v_mul_f32_e32 v18, v8, v8
	v_max_f32_e32 v8, 0, v13
	v_mul_f32_e32 v13, v9, v9
	v_max_f32_e32 v9, 0, v14
	v_mul_f32_e32 v14, v10, v10
	v_max_f32_e32 v10, 0, v15
	v_mul_f32_e32 v12, v12, v12
	v_mul_f32_e32 v8, v8, v8
	v_max_f32_e32 v11, 0, v11
	v_mul_f32_e32 v9, v9, v9
	v_mul_f32_e32 v10, v10, v10
	v_cvt_pk_bf16_f32 v8, v12, v8
	v_add_co_u32_e32 v12, vcc, s68, v144
	v_max_f32_e32 v0, 0, v0
	v_max_f32_e32 v1, 0, v1
	v_max_f32_e32 v2, 0, v2
	v_mul_f32_e32 v11, v11, v11
	v_cvt_pk_bf16_f32 v9, v9, v10
	v_cvt_pk_bf16_f32 v10, v18, v13
	v_addc_co_u32_e32 v13, vcc, 0, v145, vcc
	v_cvt_pk_bf16_f32 v11, v14, v11
	global_store_dwordx4 v[12:13], v[8:11], off
	v_max_f32_e32 v3, 0, v3
	v_max_f32_e32 v4, 0, v4
	v_mul_f32_e32 v8, v0, v0
	v_max_f32_e32 v0, 0, v5
	v_mul_f32_e32 v5, v1, v1
	v_max_f32_e32 v1, 0, v6
	v_mul_f32_e32 v6, v2, v2
	v_max_f32_e32 v2, 0, v7
	v_lshl_add_u64 v[16:17], v[144:145], 0, s[20:21]
	v_mul_f32_e32 v0, v0, v0
	v_mul_f32_e32 v1, v1, v1
	v_mul_f32_e32 v2, v2, v2
	v_mul_f32_e32 v3, v3, v3
	s_and_b64 vcc, exec, s[4:5]
	s_mov_b32 s69, s22
	s_mov_b32 s38, s24
	s_mov_b64 s[40:41], s[0:1]
	s_mov_b64 s[42:43], s[36:37]
	v_mul_f32_e32 v4, v4, v4
	v_cvt_pk_bf16_f32 v0, v4, v0
	v_cvt_pk_bf16_f32 v1, v1, v2
	v_cvt_pk_bf16_f32 v2, v8, v5
	v_cvt_pk_bf16_f32 v3, v6, v3
	global_store_dwordx4 v[16:17], v[0:3], off offset:256
	s_cbranch_vccz .LBB0_428
	s_waitcnt vmcnt(0)
	s_cmpk_gt_u32 s46, 0xff
	s_cbranch_scc1 .LBB0_437
	s_barrier

; #define PG8_STAGE(bufoff, gbase, voff) do { _Pragma("unroll") for (int _i = 0; _i < 2; ++_i) \
;         __builtin_amdgcn_global_load_lds((const unsigned*)((const char*)(gbase) + (voff)[_i]), (LAS unsigned*)(lds + (bufoff) + ldsw + _i * 8192), 16, 0, 0); } while (0)
; #define PG8_LDA(dst, b, h) do { _Pragma("unroll") for (int m = 0; m < 4; ++m) _Pragma("unroll") for (int k = 0; k < 2; ++k) dst[m][k] = *(const LAS bf16x8*)(lds + PG8_SA(b, h) + aoff + m * 2048 + k * 1024); } while (0)
; #define PG8_LDB(dst, b, h) do { _Pragma("unroll") for (int n = 0; n < 2; ++n) _Pragma("unroll") for (int k = 0; k < 2; ++k) dst[n][k] = *(const LAS bf16x8*)(lds + PG8_SB(b, h) + boff + n * 2048 + k * 1024); } while (0)
; #define PG8_MMA(ai, bj, At, Bt) do { __builtin_amdgcn_s_setprio(1); _Pragma("unroll") for (int m = 0; m < 4; ++m) _Pragma("unroll") for (int n = 0; n < 2; ++n) _Pragma("unroll") for (int k = 0; k < 2; ++k) \
;         acc[ai][bj][m][n] = __builtin_amdgcn_mfma_f32_16x16x32_bf16(Bt[n][k], At[m][k], acc[ai][bj][m][n], 0, 0, 0); __builtin_amdgcn_s_setprio(0); } while (0)
; #define PG8_WAIT_L(n) asm volatile("s_waitcnt lgkmcnt(" #n ")" ::: "memory")
; #define PG8_BAR __builtin_amdgcn_s_barrier()
; #define PG8_SCHED __builtin_amdgcn_sched_barrier(0)
; template <class Epi, class Ptrs>
; __device__ __forceinline__ void gemm_phase(LAS unsigned char* lds, const int K, const StaticOrder& S, const Ptrs& P, const Epi& E) {
;     ...
;         for (int t = 0; t < nt; t += 2) {
;             const bool last = (t == nt - 2);
;             const char* a1 = cA + (size_t)(t + 1) * kstep;
;             const char* a2 = last ? nA : cA + (size_t)(t + 2) * kstep; const char* b2 = last ? nB : cB + (size_t)(t + 2) * kstep;
;             const char* a3 = a2 + kstep; const char* b3 = b2 + kstep;
;             PG8_LDB(B0, 0, 0); PG8_SCHED; PG8_LDA(At, 0, 0); PG8_STAGE(PG8_SA(1, 1), a1 + hstep, voffA);
;             PG8_WAIT_L(8); PG8_BAR; PG8_WAIT_L(0); PG8_MMA(0, 0, At, B0); PG8_BAR; PG8_SCHED;
;             PG8_LDB(B1, 0, 1); PG8_STAGE(PG8_SB(0, 0), b2, voffB);
;             PG8_BAR; PG8_WAIT_L(0); PG8_MMA(0, 1, At, B1); PG8_BAR;
;             PG8_LDA(At, 0, 1); PG8_STAGE(PG8_SA(0, 0), a2, voffA);
;             PG8_BAR; PG8_WAIT_L(0); PG8_MMA(1, 0, At, B0); PG8_BAR; PG8_SCHED;
;             PG8_STAGE(PG8_SB(0, 1), b2 + hstep, voffB);
.LBB0_522:
	ds_read_b128 v[128:131], v193
	ds_read_b128 v[132:135], v193 offset:1024
	ds_read_b128 v[136:139], v193 offset:2048
	ds_read_b128 v[140:143], v193 offset:3072
	s_add_u32 s22, s20, 0xfff00080
	s_addc_u32 s23, s21, -1
	s_cmp_eq_u32 s46, 60
	s_cselect_b32 s25, s5, s23
	s_cselect_b32 s24, s4, s22
	s_cselect_b32 s23, s15, s13
	s_cselect_b32 s22, s14, s11
	s_add_i32 m0, s17, 0xc000
	ds_read_b128 v[144:147], v194
	ds_read_b128 v[148:151], v194 offset:1024
	ds_read_b128 v[152:155], v194 offset:2048
	ds_read_b128 v[156:159], v194 offset:3072
	ds_read_b128 v[176:179], v194 offset:4096
	ds_read_b128 v[180:183], v194 offset:5120
	ds_read_b128 v[196:199], v194 offset:6144
	ds_read_b128 v[200:203], v194 offset:7168
	global_load_lds_dwordx4 v168, s[20:21]
	s_add_i32 m0, s17, 0xe000
	s_nop 0
	global_load_lds_dwordx4 v170, s[20:21]
	s_waitcnt lgkmcnt(8)
	s_barrier
	s_waitcnt lgkmcnt(0)
	s_setprio 1
	s_waitcnt lgkmcnt(0)
	v_mfma_f32_16x16x32_bf16 v[124:127], v[128:131], v[144:147], v[124:127]
	v_mfma_f32_16x16x32_bf16 v[124:127], v[132:135], v[148:151], v[124:127]
	v_mfma_f32_16x16x32_bf16 v[120:123], v[140:143], v[148:151], v[120:123]
	v_mfma_f32_16x16x32_bf16 v[120:123], v[136:139], v[144:147], v[120:123]
	v_mfma_f32_16x16x32_bf16 v[104:107], v[136:139], v[152:155], v[104:107]
	v_mfma_f32_16x16x32_bf16 v[104:107], v[140:143], v[156:159], v[104:107]
	v_mfma_f32_16x16x32_bf16 v[112:115], v[132:135], v[156:159], v[112:115]
	v_mfma_f32_16x16x32_bf16 v[112:115], v[128:131], v[152:155], v[112:115]
	v_mfma_f32_16x16x32_bf16 v[92:95], v[128:131], v[176:179], v[92:95]
	v_mfma_f32_16x16x32_bf16 v[92:95], v[132:135], v[180:183], v[92:95]
	v_mfma_f32_16x16x32_bf16 v[88:91], v[140:143], v[180:183], v[88:91]
	v_mfma_f32_16x16x32_bf16 v[88:91], v[136:139], v[176:179], v[88:91]
	v_mfma_f32_16x16x32_bf16 v[72:75], v[136:139], v[196:199], v[72:75]
	v_mfma_f32_16x16x32_bf16 v[72:75], v[140:143], v[200:203], v[72:75]
	v_mfma_f32_16x16x32_bf16 v[76:79], v[132:135], v[200:203], v[76:79]
	v_mfma_f32_16x16x32_bf16 v[76:79], v[128:131], v[196:199], v[76:79]
	s_setprio 0
	s_barrier
	s_add_i32 s47, s42, s34
	v_lshl_add_u64 v[184:185], s[22:23], 0, v[162:163]
	s_mov_b32 m0, s47
	ds_read_b128 v[204:207], v195
	ds_read_b128 v[208:211], v195 offset:1024
	ds_read_b128 v[212:215], v195 offset:2048
	ds_read_b128 v[216:219], v195 offset:3072
	global_load_lds_dwordx4 v[184:185], off
	v_lshl_add_u64 v[220:221], s[22:23], 0, v[166:167]
	s_add_i32 m0, s47, 0x2000
	s_nop 0
	global_load_lds_dwordx4 v[220:221], off
	s_barrier
	s_waitcnt lgkmcnt(0)
	s_setprio 1
	s_waitcnt lgkmcnt(0)
	v_mfma_f32_16x16x32_bf16 v[116:119], v[204:207], v[144:147], v[116:119]
	v_mfma_f32_16x16x32_bf16 v[116:119], v[208:211], v[148:151], v[116:119]
	v_mfma_f32_16x16x32_bf16 v[108:111], v[216:219], v[148:151], v[108:111]
	v_mfma_f32_16x16x32_bf16 v[108:111], v[212:215], v[144:147], v[108:111]
	v_mfma_f32_16x16x32_bf16 v[96:99], v[212:215], v[152:155], v[96:99]
	v_mfma_f32_16x16x32_bf16 v[96:99], v[216:219], v[156:159], v[96:99]
	v_mfma_f32_16x16x32_bf16 v[100:103], v[208:211], v[156:159], v[100:103]
	v_mfma_f32_16x16x32_bf16 v[100:103], v[204:207], v[152:155], v[100:103]
	v_mfma_f32_16x16x32_bf16 v[84:87], v[204:207], v[176:179], v[84:87]
	v_mfma_f32_16x16x32_bf16 v[84:87], v[208:211], v[180:183], v[84:87]
	v_mfma_f32_16x16x32_bf16 v[80:83], v[216:219], v[180:183], v[80:83]
	v_mfma_f32_16x16x32_bf16 v[80:83], v[212:215], v[176:179], v[80:83]
	v_mfma_f32_16x16x32_bf16 v[64:67], v[212:215], v[196:199], v[64:67]
	v_mfma_f32_16x16x32_bf16 v[64:67], v[216:219], v[200:203], v[64:67]
	v_mfma_f32_16x16x32_bf16 v[68:71], v[208:211], v[200:203], v[68:71]
	v_mfma_f32_16x16x32_bf16 v[68:71], v[204:207], v[196:199], v[68:71]
	s_setprio 0
	s_mov_b32 m0, s17
	v_lshl_add_u64 v[222:223], s[24:25], 0, v[160:161]
	s_barrier
	ds_read_b128 v[144:147], v194 offset:16384
	ds_read_b128 v[148:151], v194 offset:17408
	ds_read_b128 v[152:155], v194 offset:18432
	ds_read_b128 v[156:159], v194 offset:19456
	ds_read_b128 v[176:179], v194 offset:20480
	ds_read_b128 v[180:183], v194 offset:21504
	ds_read_b128 v[196:199], v194 offset:22528
	ds_read_b128 v[200:203], v194 offset:23552
	global_load_lds_dwordx4 v[222:223], off
	v_lshl_add_u64 v[224:225], s[24:25], 0, v[164:165]
	s_mov_b32 m0, s19
	s_nop 0
	global_load_lds_dwordx4 v[224:225], off
	s_barrier
	s_waitcnt lgkmcnt(0)
	s_setprio 1
	s_waitcnt lgkmcnt(0)
	v_mfma_f32_16x16x32_bf16 v[60:63], v[128:131], v[144:147], v[60:63]
	v_mfma_f32_16x16x32_bf16 v[60:63], v[132:135], v[148:151], v[60:63]
	v_mfma_f32_16x16x32_bf16 v[56:59], v[140:143], v[148:151], v[56:59]
	v_mfma_f32_16x16x32_bf16 v[56:59], v[136:139], v[144:147], v[56:59]
	v_mfma_f32_16x16x32_bf16 v[40:43], v[136:139], v[152:155], v[40:43]
	v_mfma_f32_16x16x32_bf16 v[40:43], v[140:143], v[156:159], v[40:43]
	v_mfma_f32_16x16x32_bf16 v[48:51], v[132:135], v[156:159], v[48:51]
	v_mfma_f32_16x16x32_bf16 v[48:51], v[128:131], v[152:155], v[48:51]
	v_mfma_f32_16x16x32_bf16 v[32:35], v[128:131], v[176:179], v[32:35]
	v_mfma_f32_16x16x32_bf16 v[32:35], v[132:135], v[180:183], v[32:35]
	v_mfma_f32_16x16x32_bf16 v[24:27], v[140:143], v[180:183], v[24:27]
	v_mfma_f32_16x16x32_bf16 v[24:27], v[136:139], v[176:179], v[24:27]
	v_mfma_f32_16x16x32_bf16 v[8:11], v[136:139], v[196:199], v[8:11]
	v_mfma_f32_16x16x32_bf16 v[8:11], v[140:143], v[200:203], v[8:11]
	v_mfma_f32_16x16x32_bf16 v[16:19], v[132:135], v[200:203], v[16:19]
	v_mfma_f32_16x16x32_bf16 v[16:19], v[128:131], v[196:199], v[16:19]
	s_setprio 0
	s_barrier
	s_add_u32 s48, s22, 0x100000
	s_addc_u32 s49, s23, 0
	s_add_i32 s47, s43, s34
	s_mov_b32 m0, s47
	s_nop 0
	global_load_lds_dwordx4 v162, s[48:49]
	s_add_i32 m0, s47, 0x2000
	s_nop 0
	global_load_lds_dwordx4 v166, s[48:49]
	s_waitcnt vmcnt(6)
	s_barrier
; #define PG8_STAGE(bufoff, gbase, voff) do { _Pragma("unroll") for (int _i = 0; _i < 2; ++_i) \
;         __builtin_amdgcn_global_load_lds((const unsigned*)((const char*)(gbase) + (voff)[_i]), (LAS unsigned*)(lds + (bufoff) + ldsw + _i * 8192), 16, 0, 0); } while (0)
; #define PG8_LDA(dst, b, h) do { _Pragma("unroll") for (int m = 0; m < 4; ++m) _Pragma("unroll") for (int k = 0; k < 2; ++k) dst[m][k] = *(const LAS bf16x8*)(lds + PG8_SA(b, h) + aoff + m * 2048 + k * 1024); } while (0)
; #define PG8_LDB(dst, b, h) do { _Pragma("unroll") for (int n = 0; n < 2; ++n) _Pragma("unroll") for (int k = 0; k < 2; ++k) dst[n][k] = *(const LAS bf16x8*)(lds + PG8_SB(b, h) + boff + n * 2048 + k * 1024); } while (0)
; #define PG8_MMA(ai, bj, At, Bt) do { __builtin_amdgcn_s_setprio(1); _Pragma("unroll") for (int m = 0; m < 4; ++m) _Pragma("unroll") for (int n = 0; n < 2; ++n) _Pragma("unroll") for (int k = 0; k < 2; ++k) \
;         acc[ai][bj][m][n] = __builtin_amdgcn_mfma_f32_16x16x32_bf16(Bt[n][k], At[m][k], acc[ai][bj][m][n], 0, 0, 0); __builtin_amdgcn_s_setprio(0); } while (0)
; #define PG8_WAIT_V(n) asm volatile("s_waitcnt vmcnt(" #n ")" ::: "memory")
; #define PG8_WAIT_L(n) asm volatile("s_waitcnt lgkmcnt(" #n ")" ::: "memory")
; #define PG8_BAR __builtin_amdgcn_s_barrier()
; #define PG8_SCHED __builtin_amdgcn_sched_barrier(0)
; template <class Epi, class Ptrs>
; __device__ __forceinline__ void gemm_phase(LAS unsigned char* lds, const int K, const StaticOrder& S, const Ptrs& P, const Epi& E) {
;     ...
;             PG8_WAIT_V(6); PG8_BAR; PG8_MMA(1, 1, At, B1); PG8_BAR;
;             PG8_LDB(B0, 1, 0); PG8_SCHED; PG8_LDA(At, 1, 0); PG8_STAGE(PG8_SA(0, 1), a2 + hstep, voffA);
;             PG8_WAIT_L(8); PG8_BAR; PG8_WAIT_L(0); PG8_MMA(0, 0, At, B0); PG8_BAR; PG8_SCHED;
;             PG8_LDB(B1, 1, 1); PG8_STAGE(PG8_SB(1, 0), b3, voffB);
;             PG8_BAR; PG8_WAIT_L(0); PG8_MMA(0, 1, At, B1); PG8_BAR;
;             PG8_LDA(At, 1, 1); PG8_STAGE(PG8_SA(1, 0), a3, voffA);
	s_setprio 1
	v_mfma_f32_16x16x32_bf16 v[52:55], v[204:207], v[144:147], v[52:55]
	v_mfma_f32_16x16x32_bf16 v[52:55], v[208:211], v[148:151], v[52:55]
	v_mfma_f32_16x16x32_bf16 v[44:47], v[216:219], v[148:151], v[44:47]
	v_mfma_f32_16x16x32_bf16 v[44:47], v[212:215], v[144:147], v[44:47]
	v_mfma_f32_16x16x32_bf16 v[28:31], v[212:215], v[152:155], v[28:31]
	v_mfma_f32_16x16x32_bf16 v[28:31], v[216:219], v[156:159], v[28:31]
	v_mfma_f32_16x16x32_bf16 v[36:39], v[208:211], v[156:159], v[36:39]
	v_mfma_f32_16x16x32_bf16 v[36:39], v[204:207], v[152:155], v[36:39]
	v_mfma_f32_16x16x32_bf16 v[20:23], v[204:207], v[176:179], v[20:23]
	v_mfma_f32_16x16x32_bf16 v[20:23], v[208:211], v[180:183], v[20:23]
	v_mfma_f32_16x16x32_bf16 v[12:15], v[216:219], v[180:183], v[12:15]
	v_mfma_f32_16x16x32_bf16 v[12:15], v[212:215], v[176:179], v[12:15]
	v_mfma_f32_16x16x32_bf16 v[0:3], v[212:215], v[196:199], v[0:3]
	v_mfma_f32_16x16x32_bf16 v[0:3], v[216:219], v[200:203], v[0:3]
	v_mfma_f32_16x16x32_bf16 v[4:7], v[208:211], v[200:203], v[4:7]
	v_mfma_f32_16x16x32_bf16 v[4:7], v[204:207], v[196:199], v[4:7]
	s_setprio 0
	s_add_i32 s47, 0, 0x18000
	v_add_u32_e32 v140, s47, v187
	s_barrier
	ds_read_b128 v[128:131], v140
	ds_read_b128 v[132:135], v140 offset:1024
	ds_read_b128 v[136:139], v140 offset:2048
	ds_read_b128 v[140:143], v140 offset:3072
	s_add_u32 s24, s24, 0x100000
	s_addc_u32 s25, s25, 0
	s_mov_b32 m0, s40
	ds_read_b128 v[144:147], v194 offset:32768
	ds_read_b128 v[148:151], v194 offset:33792
	ds_read_b128 v[152:155], v194 offset:34816
	ds_read_b128 v[156:159], v194 offset:35840
	ds_read_b128 v[176:179], v194 offset:36864
	ds_read_b128 v[180:183], v194 offset:37888
	ds_read_b128 v[196:199], v194 offset:38912
	ds_read_b128 v[200:203], v194 offset:39936
	global_load_lds_dwordx4 v160, s[24:25]
	s_mov_b32 m0, s41
	s_nop 0
	global_load_lds_dwordx4 v164, s[24:25]
	s_waitcnt lgkmcnt(8)
	s_barrier
	s_waitcnt lgkmcnt(0)
	s_setprio 1
	s_waitcnt lgkmcnt(0)
	v_mfma_f32_16x16x32_bf16 v[124:127], v[128:131], v[144:147], v[124:127]
	v_mfma_f32_16x16x32_bf16 v[124:127], v[132:135], v[148:151], v[124:127]
	v_mfma_f32_16x16x32_bf16 v[120:123], v[140:143], v[148:151], v[120:123]
	v_mfma_f32_16x16x32_bf16 v[120:123], v[136:139], v[144:147], v[120:123]
	v_mfma_f32_16x16x32_bf16 v[104:107], v[136:139], v[152:155], v[104:107]
	v_mfma_f32_16x16x32_bf16 v[104:107], v[140:143], v[156:159], v[104:107]
	v_mfma_f32_16x16x32_bf16 v[112:115], v[132:135], v[156:159], v[112:115]
	v_mfma_f32_16x16x32_bf16 v[112:115], v[128:131], v[152:155], v[112:115]
	v_mfma_f32_16x16x32_bf16 v[92:95], v[128:131], v[176:179], v[92:95]
	v_mfma_f32_16x16x32_bf16 v[92:95], v[132:135], v[180:183], v[92:95]
	v_mfma_f32_16x16x32_bf16 v[88:91], v[140:143], v[180:183], v[88:91]
	v_mfma_f32_16x16x32_bf16 v[88:91], v[136:139], v[176:179], v[88:91]
	v_mfma_f32_16x16x32_bf16 v[72:75], v[136:139], v[196:199], v[72:75]
	v_mfma_f32_16x16x32_bf16 v[72:75], v[140:143], v[200:203], v[72:75]
	v_mfma_f32_16x16x32_bf16 v[76:79], v[132:135], v[200:203], v[76:79]
	v_mfma_f32_16x16x32_bf16 v[76:79], v[128:131], v[196:199], v[76:79]
	s_setprio 0
	s_barrier
	s_add_i32 s24, 0, 0x1c000
	s_add_i32 s25, s47, s34
	v_add_u32_e32 v216, s24, v187
	v_lshl_add_u64 v[184:185], v[184:185], 0, s[8:9]
	s_mov_b32 m0, s25
	ds_read_b128 v[204:207], v216
	ds_read_b128 v[208:211], v216 offset:1024
	ds_read_b128 v[212:215], v216 offset:2048
	ds_read_b128 v[216:219], v216 offset:3072
	global_load_lds_dwordx4 v[184:185], off
	v_lshl_add_u64 v[184:185], v[220:221], 0, s[8:9]
	s_add_i32 m0, s25, 0x2000
	s_nop 0
	global_load_lds_dwordx4 v[184:185], off
	s_barrier
	s_waitcnt lgkmcnt(0)
	s_setprio 1
	s_waitcnt lgkmcnt(0)
	v_mfma_f32_16x16x32_bf16 v[116:119], v[204:207], v[144:147], v[116:119]
	v_mfma_f32_16x16x32_bf16 v[116:119], v[208:211], v[148:151], v[116:119]
	v_mfma_f32_16x16x32_bf16 v[108:111], v[216:219], v[148:151], v[108:111]
	v_mfma_f32_16x16x32_bf16 v[108:111], v[212:215], v[144:147], v[108:111]
	v_mfma_f32_16x16x32_bf16 v[96:99], v[212:215], v[152:155], v[96:99]
	v_mfma_f32_16x16x32_bf16 v[96:99], v[216:219], v[156:159], v[96:99]
	v_mfma_f32_16x16x32_bf16 v[100:103], v[208:211], v[156:159], v[100:103]
	v_mfma_f32_16x16x32_bf16 v[100:103], v[204:207], v[152:155], v[100:103]
	v_mfma_f32_16x16x32_bf16 v[84:87], v[204:207], v[176:179], v[84:87]
	v_mfma_f32_16x16x32_bf16 v[84:87], v[208:211], v[180:183], v[84:87]
	v_mfma_f32_16x16x32_bf16 v[80:83], v[216:219], v[180:183], v[80:83]
	v_mfma_f32_16x16x32_bf16 v[80:83], v[212:215], v[176:179], v[80:83]
	v_mfma_f32_16x16x32_bf16 v[64:67], v[212:215], v[196:199], v[64:67]
	v_mfma_f32_16x16x32_bf16 v[64:67], v[216:219], v[200:203], v[64:67]
	v_mfma_f32_16x16x32_bf16 v[68:71], v[208:211], v[200:203], v[68:71]
	v_mfma_f32_16x16x32_bf16 v[68:71], v[204:207], v[196:199], v[68:71]
	s_setprio 0
	s_mov_b32 m0, s28
	v_lshl_add_u64 v[184:185], v[222:223], 0, s[8:9]
	s_barrier
	ds_read_b128 v[144:147], v194 offset:49152
	ds_read_b128 v[148:151], v194 offset:50176
	ds_read_b128 v[152:155], v194 offset:51200
	ds_read_b128 v[156:159], v194 offset:52224
	ds_read_b128 v[176:179], v194 offset:53248
	ds_read_b128 v[180:183], v194 offset:54272
	ds_read_b128 v[196:199], v194 offset:55296
	ds_read_b128 v[200:203], v194 offset:56320
	global_load_lds_dwordx4 v[184:185], off
	v_lshl_add_u64 v[184:185], v[224:225], 0, s[8:9]
	s_mov_b32 m0, s29
	s_nop 0
	global_load_lds_dwordx4 v[184:185], off
	s_barrier
; __device__ __forceinline__ float bf_lo(unsigned w) { return __uint_as_float(w << 16); }
; __device__ __forceinline__ float bf_hi(unsigned w) { return __uint_as_float(w & 0xffff0000u); }
; #define PG8_STAGE(bufoff, gbase, voff) do { _Pragma("unroll") for (int _i = 0; _i < 2; ++_i) \
;         __builtin_amdgcn_global_load_lds((const unsigned*)((const char*)(gbase) + (voff)[_i]), (LAS unsigned*)(lds + (bufoff) + ldsw + _i * 8192), 16, 0, 0); } while (0)
; #define PG8_WAIT_V(n) asm volatile("s_waitcnt vmcnt(" #n ")" ::: "memory")
; #define PG8_WAIT_L(n) asm volatile("s_waitcnt lgkmcnt(" #n ")" ::: "memory")
; #define PG8_BAR __builtin_amdgcn_s_barrier()
; #define PG8_SCHED __builtin_amdgcn_sched_barrier(0)
; template <class Epi, class Ptrs>
; __device__ __forceinline__ void gemm_phase(LAS unsigned char* lds, const int K, const StaticOrder& S, const Ptrs& P, const Epi& E) {
;     ...
;             PG8_BAR; PG8_WAIT_L(0); PG8_MMA(1, 0, At, B0); PG8_BAR; PG8_SCHED;
;             PG8_STAGE(PG8_SB(1, 1), b3 + hstep, voffB);
;             PG8_WAIT_V(6); PG8_BAR; PG8_MMA(1, 1, At, B1); PG8_BAR;
;         }
;     __device__ __forceinline__ void operator()(const f32x4 (&acc)[2][2][4][2], const Unit& u, int ui, int wr, int wc, int fr, int fq) const {
;         const int rl0 = wr * 64 + fr, col0 = u.pn * 256 + wc * 32 + 8 * fq;
;         u32x4 xv[2][4][2];
; #pragma unroll
;         for (int ai = 0; ai < 2; ++ai)
; #pragma unroll
;             for (int m = 0; m < 4; ++m)
; #pragma unroll
;                 for (int bj = 0; bj < 2; ++bj) xv[ai][m][bj] = *(const u32x4*)(xb + (size_t)(u.pm * 256 + rl0 + ai * 128 + m * 16) * DM + col0 + bj * 128);
; #pragma unroll
;         for (int ai = 0; ai < 2; ++ai)
; #pragma unroll
;             for (int m = 0; m < 4; ++m) { const int rl = rl0 + ai * 128 + m * 16; float* rowp = out + (size_t)(u.pm * 256 + rl) * DM + col0;
;                 const float r2 = tab[ui * 256 + rl];
; #pragma unroll
;                 for (int bj = 0; bj < 2; ++bj) { const u32x4 x = xv[ai][m][bj];
;                     const f32x4 x0 = {bf_lo(x.x), bf_hi(x.x), bf_lo(x.y), bf_hi(x.y)}, x1 = {bf_lo(x.z), bf_hi(x.z), bf_lo(x.w), bf_hi(x.w)};
;                     *(f32x4*)(rowp + bj * 128) = acc[ai][bj][m][0] * r2 + x0; *(f32x4*)(rowp + bj * 128 + 4) = acc[ai][bj][m][1] * r2 + x1; } }
	s_waitcnt lgkmcnt(0)
	s_setprio 1
	s_waitcnt lgkmcnt(0)
	v_mfma_f32_16x16x32_bf16 v[60:63], v[128:131], v[144:147], v[60:63]
	v_mfma_f32_16x16x32_bf16 v[60:63], v[132:135], v[148:151], v[60:63]
	v_mfma_f32_16x16x32_bf16 v[56:59], v[140:143], v[148:151], v[56:59]
	v_mfma_f32_16x16x32_bf16 v[56:59], v[136:139], v[144:147], v[56:59]
	v_mfma_f32_16x16x32_bf16 v[40:43], v[136:139], v[152:155], v[40:43]
	v_mfma_f32_16x16x32_bf16 v[40:43], v[140:143], v[156:159], v[40:43]
	v_mfma_f32_16x16x32_bf16 v[48:51], v[132:135], v[156:159], v[48:51]
	v_mfma_f32_16x16x32_bf16 v[48:51], v[128:131], v[152:155], v[48:51]
	v_mfma_f32_16x16x32_bf16 v[32:35], v[128:131], v[176:179], v[32:35]
	v_mfma_f32_16x16x32_bf16 v[32:35], v[132:135], v[180:183], v[32:35]
	v_mfma_f32_16x16x32_bf16 v[24:27], v[140:143], v[180:183], v[24:27]
	v_mfma_f32_16x16x32_bf16 v[24:27], v[136:139], v[176:179], v[24:27]
	v_mfma_f32_16x16x32_bf16 v[8:11], v[136:139], v[196:199], v[8:11]
	v_mfma_f32_16x16x32_bf16 v[8:11], v[140:143], v[200:203], v[8:11]
	v_mfma_f32_16x16x32_bf16 v[16:19], v[132:135], v[200:203], v[16:19]
	v_mfma_f32_16x16x32_bf16 v[16:19], v[128:131], v[196:199], v[16:19]
	s_setprio 0
	s_barrier
	s_add_u32 s22, s22, 0x100080
	s_addc_u32 s23, s23, 0
	s_add_i32 s24, s24, s34
	s_mov_b32 m0, s24
	s_nop 0
	global_load_lds_dwordx4 v162, s[22:23]
	s_add_i32 m0, s24, 0x2000
	s_nop 0
	global_load_lds_dwordx4 v166, s[22:23]
	s_waitcnt vmcnt(6)
	s_barrier
	s_setprio 1
	v_mfma_f32_16x16x32_bf16 v[52:55], v[204:207], v[144:147], v[52:55]
	v_mfma_f32_16x16x32_bf16 v[52:55], v[208:211], v[148:151], v[52:55]
	v_mfma_f32_16x16x32_bf16 v[44:47], v[216:219], v[148:151], v[44:47]
	v_mfma_f32_16x16x32_bf16 v[44:47], v[212:215], v[144:147], v[44:47]
	v_mfma_f32_16x16x32_bf16 v[28:31], v[212:215], v[152:155], v[28:31]
	v_mfma_f32_16x16x32_bf16 v[28:31], v[216:219], v[156:159], v[28:31]
	v_mfma_f32_16x16x32_bf16 v[36:39], v[208:211], v[156:159], v[36:39]
	v_mfma_f32_16x16x32_bf16 v[36:39], v[204:207], v[152:155], v[36:39]
	v_mfma_f32_16x16x32_bf16 v[20:23], v[204:207], v[176:179], v[20:23]
	v_mfma_f32_16x16x32_bf16 v[20:23], v[208:211], v[180:183], v[20:23]
	v_mfma_f32_16x16x32_bf16 v[12:15], v[216:219], v[180:183], v[12:15]
	v_mfma_f32_16x16x32_bf16 v[12:15], v[212:215], v[176:179], v[12:15]
	v_mfma_f32_16x16x32_bf16 v[0:3], v[212:215], v[196:199], v[0:3]
	v_mfma_f32_16x16x32_bf16 v[0:3], v[216:219], v[200:203], v[0:3]
	v_mfma_f32_16x16x32_bf16 v[4:7], v[208:211], v[200:203], v[4:7]
	v_mfma_f32_16x16x32_bf16 v[4:7], v[204:207], v[196:199], v[4:7]
	s_setprio 0
	s_add_i32 s46, s46, 2
	s_add_u32 s20, s20, 0x100
	s_addc_u32 s21, s21, 0
	s_add_u32 s11, s11, 0x100
	s_addc_u32 s13, s13, 0
	s_cmp_gt_u32 s46, 61
	s_barrier
	s_cbranch_scc0 .LBB0_522
	s_nop 0
	s_nop 0
	s_nop 0
	s_nop 0
	s_nop 0
	s_nop 0
	s_nop 0
	s_nop 0
	s_nop 0
	s_nop 0
	s_nop 0
	s_nop 0
	s_nop 0
	s_nop 0
	s_nop 0
	s_nop 0
	s_lshl_b32 s11, s18, 8
	v_lshl_or_b32 v128, s16, 8, v191
	v_add_u32_e32 v130, s11, v186
	v_ashrrev_i32_e32 v129, 31, v128
	v_ashrrev_i32_e32 v131, 31, v130
	v_lshl_add_u64 v[132:133], v[128:129], 1, s[6:7]
	v_lshlrev_b64 v[134:135], 11, v[130:131]
	v_lshl_add_u64 v[134:135], v[132:133], 0, v[134:135]
	global_load_dwordx4 v[198:201], v[134:135], off
	global_load_dwordx4 v[202:205], v[134:135], off offset:256
	v_or_b32_e32 v134, 16, v130
	v_ashrrev_i32_e32 v135, 31, v134
	v_lshlrev_b64 v[134:135], 11, v[134:135]
	v_lshl_add_u64 v[134:135], v[132:133], 0, v[134:135]
	global_load_dwordx4 v[206:209], v[134:135], off
	global_load_dwordx4 v[210:213], v[134:135], off offset:256
	v_or_b32_e32 v136, 32, v130
	v_ashrrev_i32_e32 v137, 31, v136
	v_or_b32_e32 v138, 48, v130
	v_add_u32_e32 v184, 0x80, v130
	v_add_u32_e32 v182, 0x90, v130
	v_add_u32_e32 v180, 0xa0, v130
	v_add_u32_e32 v178, 0xb0, v130
	v_lshlrev_b64 v[176:177], 2, v[128:129]
	v_lshlrev_b64 v[128:129], 12, v[130:131]
	v_lshlrev_b64 v[130:131], 11, v[136:137]
	v_lshl_add_u64 v[130:131], v[132:133], 0, v[130:131]
	global_load_dwordx4 v[214:217], v[130:131], off
	v_ashrrev_i32_e32 v139, 31, v138
	v_ashrrev_i32_e32 v185, 31, v184
	v_ashrrev_i32_e32 v183, 31, v182
	v_ashrrev_i32_e32 v181, 31, v180
	v_ashrrev_i32_e32 v179, 31, v178
	v_lshlrev_b64 v[134:135], 11, v[138:139]
	v_lshlrev_b64 v[136:137], 11, v[184:185]
	v_lshlrev_b64 v[138:139], 11, v[182:183]
	v_lshl_add_u32 v196, s45, 10, v192
	v_lshlrev_b64 v[140:141], 11, v[180:181]
	v_lshlrev_b64 v[142:143], 11, v[178:179]
	v_lshl_add_u64 v[128:129], s[26:27], 0, v[128:129]
	v_lshl_add_u64 v[134:135], v[132:133], 0, v[134:135]
	v_lshl_add_u64 v[136:137], v[132:133], 0, v[136:137]
	v_lshl_add_u64 v[138:139], v[132:133], 0, v[138:139]
	ds_read2_b32 v[230:231], v196 offset1:16
	v_lshl_add_u64 v[234:235], v[132:133], 0, v[140:141]
	v_lshl_add_u64 v[236:237], v[132:133], 0, v[142:143]
	v_lshl_add_u64 v[238:239], v[128:129], 0, v[176:177]
	global_load_dwordx4 v[218:221], v[130:131], off offset:256
	global_load_dwordx4 v[222:225], v[134:135], off
	global_load_dwordx4 v[226:229], v[134:135], off offset:256
	global_load_dwordx4 v[156:159], v[136:137], off
	global_load_dwordx4 v[152:155], v[136:137], off offset:256
	global_load_dwordx4 v[148:151], v[138:139], off
	global_load_dwordx4 v[144:147], v[138:139], off offset:256
	global_load_dwordx4 v[140:143], v[234:235], off
	s_nop 0
	global_load_dwordx4 v[136:139], v[234:235], off offset:256
	global_load_dwordx4 v[132:135], v[236:237], off
	global_load_dwordx4 v[128:131], v[236:237], off offset:256
	v_add_u32_e32 v232, s11, v188
	v_ashrrev_i32_e32 v233, 31, v232
	s_and_b64 vcc, exec, s[0:1]
	s_mov_b32 s16, s10
	s_mov_b32 s18, s12
	s_mov_b64 s[20:21], s[4:5]
	s_mov_b64 s[22:23], s[14:15]
	s_mov_b32 s45, s44
	s_waitcnt vmcnt(0)
; __device__ __forceinline__ float bf_lo(unsigned w) { return __uint_as_float(w << 16); }
; __device__ __forceinline__ float bf_hi(unsigned w) { return __uint_as_float(w & 0xffff0000u); }
;     __device__ __forceinline__ void operator()(const f32x4 (&acc)[2][2][4][2], const Unit& u, int ui, int wr, int wc, int fr, int fq) const {
;     ...
;         for (int ai = 0; ai < 2; ++ai)
; #pragma unroll
;             for (int m = 0; m < 4; ++m) { const int rl = rl0 + ai * 128 + m * 16; float* rowp = out + (size_t)(u.pm * 256 + rl) * DM + col0;
;                 const float r2 = tab[ui * 256 + rl];
; #pragma unroll
;                 for (int bj = 0; bj < 2; ++bj) { const u32x4 x = xv[ai][m][bj];
;                     const f32x4 x0 = {bf_lo(x.x), bf_hi(x.x), bf_lo(x.y), bf_hi(x.y)}, x1 = {bf_lo(x.z), bf_hi(x.z), bf_lo(x.w), bf_hi(x.w)};
;                     *(f32x4*)(rowp + bj * 128) = acc[ai][bj][m][0] * r2 + x0; *(f32x4*)(rowp + bj * 128 + 4) = acc[ai][bj][m][1] * r2 + x1; } }
	v_lshlrev_b32_e32 v234, 16, v198
	v_and_b32_e32 v235, 0xffff0000, v198
	v_lshlrev_b32_e32 v198, 16, v199
	v_and_b32_e32 v199, 0xffff0000, v199
	v_lshlrev_b32_e32 v242, 16, v204
	v_and_b32_e32 v243, 0xffff0000, v204
	v_lshlrev_b32_e32 v236, 16, v200
	v_and_b32_e32 v237, 0xffff0000, v200
	v_lshlrev_b32_e32 v200, 16, v201
	v_and_b32_e32 v201, 0xffff0000, v201
	v_lshlrev_b32_e32 v240, 16, v202
	v_and_b32_e32 v241, 0xffff0000, v202
	v_lshlrev_b32_e32 v202, 16, v203
	v_and_b32_e32 v203, 0xffff0000, v203
	v_lshlrev_b32_e32 v204, 16, v205
	v_and_b32_e32 v205, 0xffff0000, v205
	s_waitcnt lgkmcnt(0)
	v_pk_fma_f32 v[126:127], v[126:127], v[230:231], v[198:199] op_sel_hi:[1,0,1]
	v_pk_fma_f32 v[124:125], v[124:125], v[230:231], v[234:235] op_sel_hi:[1,0,1]
	v_pk_fma_f32 v[108:109], v[108:109], v[230:231], v[242:243] op_sel_hi:[1,0,1]
	v_pk_fma_f32 v[122:123], v[122:123], v[230:231], v[200:201] op_sel_hi:[1,0,1]
	v_pk_fma_f32 v[120:121], v[120:121], v[230:231], v[236:237] op_sel_hi:[1,0,1]
	v_pk_fma_f32 v[118:119], v[118:119], v[230:231], v[202:203] op_sel_hi:[1,0,1]
	v_pk_fma_f32 v[116:117], v[116:117], v[230:231], v[240:241] op_sel_hi:[1,0,1]
	v_pk_fma_f32 v[110:111], v[110:111], v[230:231], v[204:205] op_sel_hi:[1,0,1]
	global_store_dwordx4 v[238:239], v[124:127], off
	global_store_dwordx4 v[238:239], v[120:123], off offset:16
	global_store_dwordx4 v[238:239], v[116:119], off offset:512
	global_store_dwordx4 v[238:239], v[108:111], off offset:528
	v_mov_b32_e32 v122, v231
	v_lshlrev_b32_e32 v118, 16, v208
	v_lshlrev_b64 v[108:109], 12, v[232:233]
	v_lshl_add_u64 v[108:109], s[26:27], 0, v[108:109]
	v_lshl_add_u64 v[116:117], v[108:109], 0, v[176:177]
	v_lshlrev_b32_e32 v108, 16, v206
	v_and_b32_e32 v109, 0xffff0000, v206
	v_lshlrev_b32_e32 v110, 16, v207
	v_and_b32_e32 v111, 0xffff0000, v207
	v_pk_fma_f32 v[110:111], v[114:115], v[122:123], v[110:111] op_sel_hi:[1,0,1]
	v_pk_fma_f32 v[108:109], v[112:113], v[122:123], v[108:109] op_sel_hi:[1,0,1]
	global_store_dwordx4 v[116:117], v[108:111], off
	v_and_b32_e32 v119, 0xffff0000, v208
	v_lshlrev_b32_e32 v120, 16, v209
	v_lshlrev_b32_e32 v108, 16, v212
	v_and_b32_e32 v109, 0xffff0000, v212
	v_lshlrev_b32_e32 v110, 16, v213
	v_and_b32_e32 v111, 0xffff0000, v213
	v_pk_fma_f32 v[98:99], v[98:99], v[122:123], v[110:111] op_sel_hi:[1,0,1]
	v_pk_fma_f32 v[96:97], v[96:97], v[122:123], v[108:109] op_sel_hi:[1,0,1]
	v_and_b32_e32 v121, 0xffff0000, v209
	global_store_dwordx4 v[116:117], v[96:99], off offset:528
	ds_read2_b32 v[98:99], v196 offset0:32 offset1:48
	v_pk_fma_f32 v[106:107], v[106:107], v[122:123], v[120:121] op_sel_hi:[1,0,1]
	v_pk_fma_f32 v[104:105], v[104:105], v[122:123], v[118:119] op_sel_hi:[1,0,1]
	v_add_u32_e32 v96, s11, v189
	global_store_dwordx4 v[116:117], v[104:107], off offset:16
	v_ashrrev_i32_e32 v97, 31, v96
	v_lshlrev_b64 v[96:97], 12, v[96:97]
	v_lshlrev_b32_e32 v104, 16, v210
	v_and_b32_e32 v105, 0xffff0000, v210
	v_lshlrev_b32_e32 v106, 16, v211
	v_and_b32_e32 v107, 0xffff0000, v211
	v_pk_fma_f32 v[102:103], v[102:103], v[122:123], v[106:107] op_sel_hi:[1,0,1]
	v_pk_fma_f32 v[100:101], v[100:101], v[122:123], v[104:105] op_sel_hi:[1,0,1]
	global_store_dwordx4 v[116:117], v[100:103], off offset:512
	v_lshl_add_u64 v[96:97], s[26:27], 0, v[96:97]
	v_lshl_add_u64 v[96:97], v[96:97], 0, v[176:177]
	v_lshlrev_b32_e32 v100, 16, v214
	v_and_b32_e32 v101, 0xffff0000, v214
	v_lshlrev_b32_e32 v102, 16, v215
	v_and_b32_e32 v103, 0xffff0000, v215
	s_waitcnt lgkmcnt(0)
	v_pk_fma_f32 v[94:95], v[94:95], v[98:99], v[102:103] op_sel_hi:[1,0,1]
	v_pk_fma_f32 v[92:93], v[92:93], v[98:99], v[100:101] op_sel_hi:[1,0,1]
	global_store_dwordx4 v[96:97], v[92:95], off
	v_lshlrev_b32_e32 v104, 16, v216
	v_and_b32_e32 v105, 0xffff0000, v216
	v_lshlrev_b32_e32 v92, 16, v220
	v_and_b32_e32 v93, 0xffff0000, v220
	v_lshlrev_b32_e32 v94, 16, v221
	v_and_b32_e32 v95, 0xffff0000, v221
	v_lshlrev_b32_e32 v106, 16, v217
	v_and_b32_e32 v107, 0xffff0000, v217
	v_pk_fma_f32 v[82:83], v[82:83], v[98:99], v[94:95] op_sel_hi:[1,0,1]
	v_pk_fma_f32 v[80:81], v[80:81], v[98:99], v[92:93] op_sel_hi:[1,0,1]
	v_pk_fma_f32 v[90:91], v[90:91], v[98:99], v[106:107] op_sel_hi:[1,0,1]
	v_pk_fma_f32 v[88:89], v[88:89], v[98:99], v[104:105] op_sel_hi:[1,0,1]
	global_store_dwordx4 v[96:97], v[80:83], off offset:528
	global_store_dwordx4 v[96:97], v[88:91], off offset:16
	s_nop 0
	v_add_u32_e32 v80, s11, v190
	v_lshlrev_b32_e32 v88, 16, v218
	v_and_b32_e32 v89, 0xffff0000, v218
	v_lshlrev_b32_e32 v90, 16, v219
	v_and_b32_e32 v91, 0xffff0000, v219
	v_ashrrev_i32_e32 v81, 31, v80
	v_pk_fma_f32 v[86:87], v[86:87], v[98:99], v[90:91] op_sel_hi:[1,0,1]
	v_pk_fma_f32 v[84:85], v[84:85], v[98:99], v[88:89] op_sel_hi:[1,0,1]
	v_lshlrev_b64 v[80:81], 12, v[80:81]
	global_store_dwordx4 v[96:97], v[84:87], off offset:512
	v_lshl_add_u64 v[80:81], s[26:27], 0, v[80:81]
	v_lshlrev_b32_e32 v82, 16, v222
	v_and_b32_e32 v83, 0xffff0000, v222
	v_lshlrev_b32_e32 v84, 16, v223
	v_and_b32_e32 v85, 0xffff0000, v223
	v_mov_b32_e32 v90, v99
	v_lshl_add_u64 v[80:81], v[80:81], 0, v[176:177]
	v_pk_fma_f32 v[78:79], v[78:79], v[90:91], v[84:85] op_sel_hi:[1,0,1]
	v_pk_fma_f32 v[76:77], v[76:77], v[90:91], v[82:83] op_sel_hi:[1,0,1]
	global_store_dwordx4 v[80:81], v[76:79], off
	v_lshlrev_b32_e32 v86, 16, v224
	v_and_b32_e32 v87, 0xffff0000, v224
	v_lshlrev_b32_e32 v76, 16, v228
	v_and_b32_e32 v77, 0xffff0000, v228
	v_lshlrev_b32_e32 v78, 16, v229
	v_and_b32_e32 v79, 0xffff0000, v229
	v_pk_fma_f32 v[66:67], v[66:67], v[90:91], v[78:79] op_sel_hi:[1,0,1]
	v_pk_fma_f32 v[64:65], v[64:65], v[90:91], v[76:77] op_sel_hi:[1,0,1]
	v_lshlrev_b32_e32 v88, 16, v225
	v_and_b32_e32 v89, 0xffff0000, v225
	global_store_dwordx4 v[80:81], v[64:67], off offset:528
	ds_read2_b32 v[66:67], v196 offset0:128 offset1:144
	v_pk_fma_f32 v[74:75], v[74:75], v[90:91], v[88:89] op_sel_hi:[1,0,1]
	v_pk_fma_f32 v[72:73], v[72:73], v[90:91], v[86:87] op_sel_hi:[1,0,1]
	global_store_dwordx4 v[80:81], v[72:75], off offset:16
	v_lshlrev_b64 v[64:65], 12, v[184:185]
	v_lshl_add_u64 v[64:65], s[26:27], 0, v[64:65]
	v_lshlrev_b32_e32 v72, 16, v226
	v_and_b32_e32 v73, 0xffff0000, v226
	v_lshlrev_b32_e32 v74, 16, v227
	v_and_b32_e32 v75, 0xffff0000, v227
	v_pk_fma_f32 v[70:71], v[70:71], v[90:91], v[74:75] op_sel_hi:[1,0,1]
	v_pk_fma_f32 v[68:69], v[68:69], v[90:91], v[72:73] op_sel_hi:[1,0,1]
	global_store_dwordx4 v[80:81], v[68:71], off offset:512
	v_lshl_add_u64 v[64:65], v[64:65], 0, v[176:177]
	v_lshlrev_b32_e32 v72, 16, v158
	v_lshlrev_b32_e32 v68, 16, v156
	v_and_b32_e32 v69, 0xffff0000, v156
	v_lshlrev_b32_e32 v70, 16, v157
	v_and_b32_e32 v71, 0xffff0000, v157
	v_and_b32_e32 v73, 0xffff0000, v158
	v_lshlrev_b32_e32 v74, 16, v159
	v_and_b32_e32 v75, 0xffff0000, v159
	s_waitcnt lgkmcnt(0)
; __device__ __forceinline__ float bf_lo(unsigned w) { return __uint_as_float(w << 16); }
; __device__ __forceinline__ float bf_hi(unsigned w) { return __uint_as_float(w & 0xffff0000u); }
; #define PG8_WAIT_V(n) asm volatile("s_waitcnt vmcnt(" #n ")" ::: "memory")
; #define PG8_BAR __builtin_amdgcn_s_barrier()
; template <class Epi, class Ptrs>
; __device__ __forceinline__ void gemm_phase(LAS unsigned char* lds, const int K, const StaticOrder& S, const Ptrs& P, const Epi& E) {
;     ...
;         if (!has_next) break;
; #pragma unroll
;         for (int a = 0; a < 2; ++a)
; #pragma unroll
;             for (int b = 0; b < 2; ++b)
; #pragma unroll
;                 for (int m = 0; m < 4; ++m)
; #pragma unroll
;                     for (int n = 0; n < 2; ++n) acc[a][b][m][n] = (f32x4){0.f, 0.f, 0.f, 0.f};
;         cur = nxt; cA = nA; cB = nB; ++ui;
;     }
;     PG8_WAIT_V(0);
;     if (wr == 0) PG8_BAR;
;     PG8_BAR;
;     __device__ __forceinline__ void operator()(const f32x4 (&acc)[2][2][4][2], const Unit& u, int ui, int wr, int wc, int fr, int fq) const {
;     ...
;         for (int ai = 0; ai < 2; ++ai)
; #pragma unroll
;             for (int m = 0; m < 4; ++m) { const int rl = rl0 + ai * 128 + m * 16; float* rowp = out + (size_t)(u.pm * 256 + rl) * DM + col0;
;                 const float r2 = tab[ui * 256 + rl];
; #pragma unroll
;                 for (int bj = 0; bj < 2; ++bj) { const u32x4 x = xv[ai][m][bj];
;                     const f32x4 x0 = {bf_lo(x.x), bf_hi(x.x), bf_lo(x.y), bf_hi(x.y)}, x1 = {bf_lo(x.z), bf_hi(x.z), bf_lo(x.w), bf_hi(x.w)};
;                     *(f32x4*)(rowp + bj * 128) = acc[ai][bj][m][0] * r2 + x0; *(f32x4*)(rowp + bj * 128 + 4) = acc[ai][bj][m][1] * r2 + x1; } }
	v_pk_fma_f32 v[62:63], v[62:63], v[66:67], v[70:71] op_sel_hi:[1,0,1]
	v_pk_fma_f32 v[60:61], v[60:61], v[66:67], v[68:69] op_sel_hi:[1,0,1]
	global_store_dwordx4 v[64:65], v[60:63], off
	v_pk_fma_f32 v[58:59], v[58:59], v[66:67], v[74:75] op_sel_hi:[1,0,1]
	v_pk_fma_f32 v[56:57], v[56:57], v[66:67], v[72:73] op_sel_hi:[1,0,1]
	v_lshlrev_b32_e32 v60, 16, v154
	v_and_b32_e32 v61, 0xffff0000, v154
	v_lshlrev_b32_e32 v62, 16, v155
	v_and_b32_e32 v63, 0xffff0000, v155
	global_store_dwordx4 v[64:65], v[56:59], off offset:16
	v_pk_fma_f32 v[46:47], v[46:47], v[66:67], v[62:63] op_sel_hi:[1,0,1]
	v_pk_fma_f32 v[44:45], v[44:45], v[66:67], v[60:61] op_sel_hi:[1,0,1]
	v_lshlrev_b32_e32 v56, 16, v152
	v_and_b32_e32 v57, 0xffff0000, v152
	v_lshlrev_b32_e32 v58, 16, v153
	v_and_b32_e32 v59, 0xffff0000, v153
	v_pk_fma_f32 v[54:55], v[54:55], v[66:67], v[58:59] op_sel_hi:[1,0,1]
	v_pk_fma_f32 v[52:53], v[52:53], v[66:67], v[56:57] op_sel_hi:[1,0,1]
	global_store_dwordx4 v[64:65], v[44:47], off offset:528
	global_store_dwordx4 v[64:65], v[52:55], off offset:512
	v_lshlrev_b32_e32 v56, 16, v151
	v_lshlrev_b64 v[44:45], 12, v[182:183]
	v_lshl_add_u64 v[44:45], s[26:27], 0, v[44:45]
	v_lshlrev_b32_e32 v54, 16, v150
	v_and_b32_e32 v55, 0xffff0000, v150
	v_and_b32_e32 v57, 0xffff0000, v151
	v_mov_b32_e32 v58, v67
	v_lshl_add_u64 v[52:53], v[44:45], 0, v[176:177]
	v_pk_fma_f32 v[42:43], v[42:43], v[58:59], v[56:57] op_sel_hi:[1,0,1]
	v_pk_fma_f32 v[40:41], v[40:41], v[58:59], v[54:55] op_sel_hi:[1,0,1]
	v_lshlrev_b32_e32 v44, 16, v148
	v_and_b32_e32 v45, 0xffff0000, v148
	v_lshlrev_b32_e32 v46, 16, v149
	v_and_b32_e32 v47, 0xffff0000, v149
	global_store_dwordx4 v[52:53], v[40:43], off offset:16
	v_pk_fma_f32 v[46:47], v[50:51], v[58:59], v[46:47] op_sel_hi:[1,0,1]
	v_pk_fma_f32 v[44:45], v[48:49], v[58:59], v[44:45] op_sel_hi:[1,0,1]
	v_lshlrev_b32_e32 v40, 16, v144
	v_and_b32_e32 v41, 0xffff0000, v144
	v_lshlrev_b32_e32 v42, 16, v145
	v_and_b32_e32 v43, 0xffff0000, v145
	v_pk_fma_f32 v[38:39], v[38:39], v[58:59], v[42:43] op_sel_hi:[1,0,1]
	v_pk_fma_f32 v[36:37], v[36:37], v[58:59], v[40:41] op_sel_hi:[1,0,1]
	global_store_dwordx4 v[52:53], v[44:47], off
	global_store_dwordx4 v[52:53], v[36:39], off offset:512
	ds_read2_b32 v[38:39], v196 offset0:160 offset1:176
	v_lshlrev_b32_e32 v44, 16, v146
	v_and_b32_e32 v45, 0xffff0000, v146
	v_lshlrev_b32_e32 v46, 16, v147
	v_and_b32_e32 v47, 0xffff0000, v147
	v_pk_fma_f32 v[30:31], v[30:31], v[58:59], v[46:47] op_sel_hi:[1,0,1]
	v_pk_fma_f32 v[28:29], v[28:29], v[58:59], v[44:45] op_sel_hi:[1,0,1]
	global_store_dwordx4 v[52:53], v[28:31], off offset:528
	v_lshlrev_b32_e32 v40, 16, v142
	v_and_b32_e32 v41, 0xffff0000, v142
	v_lshlrev_b64 v[28:29], 12, v[180:181]
	v_lshl_add_u64 v[28:29], s[26:27], 0, v[28:29]
	v_lshl_add_u64 v[36:37], v[28:29], 0, v[176:177]
	v_lshlrev_b32_e32 v28, 16, v140
	v_and_b32_e32 v29, 0xffff0000, v140
	v_lshlrev_b32_e32 v30, 16, v141
	v_and_b32_e32 v31, 0xffff0000, v141
	s_waitcnt lgkmcnt(0)
	v_pk_fma_f32 v[30:31], v[34:35], v[38:39], v[30:31] op_sel_hi:[1,0,1]
	v_pk_fma_f32 v[28:29], v[32:33], v[38:39], v[28:29] op_sel_hi:[1,0,1]
	v_lshlrev_b32_e32 v42, 16, v143
	v_and_b32_e32 v43, 0xffff0000, v143
	global_store_dwordx4 v[36:37], v[28:31], off
	v_pk_fma_f32 v[26:27], v[26:27], v[38:39], v[42:43] op_sel_hi:[1,0,1]
	v_pk_fma_f32 v[24:25], v[24:25], v[38:39], v[40:41] op_sel_hi:[1,0,1]
	v_lshlrev_b32_e32 v28, 16, v138
	v_and_b32_e32 v29, 0xffff0000, v138
	v_lshlrev_b32_e32 v30, 16, v139
	v_and_b32_e32 v31, 0xffff0000, v139
	v_pk_fma_f32 v[14:15], v[14:15], v[38:39], v[30:31] op_sel_hi:[1,0,1]
	v_pk_fma_f32 v[12:13], v[12:13], v[38:39], v[28:29] op_sel_hi:[1,0,1]
	global_store_dwordx4 v[36:37], v[24:27], off offset:16
	global_store_dwordx4 v[36:37], v[12:15], off offset:528
	s_nop 0
	v_lshlrev_b32_e32 v24, 16, v136
	v_and_b32_e32 v25, 0xffff0000, v136
	v_lshlrev_b32_e32 v26, 16, v137
	v_and_b32_e32 v27, 0xffff0000, v137
	v_lshlrev_b64 v[12:13], 12, v[178:179]
	v_pk_fma_f32 v[22:23], v[22:23], v[38:39], v[26:27] op_sel_hi:[1,0,1]
	v_pk_fma_f32 v[20:21], v[20:21], v[38:39], v[24:25] op_sel_hi:[1,0,1]
	v_lshl_add_u64 v[12:13], s[26:27], 0, v[12:13]
	global_store_dwordx4 v[36:37], v[20:23], off offset:512
	v_lshlrev_b32_e32 v14, 16, v133
	v_and_b32_e32 v15, 0xffff0000, v133
	v_lshl_add_u64 v[20:21], v[12:13], 0, v[176:177]
	v_lshlrev_b32_e32 v12, 16, v132
	v_and_b32_e32 v13, 0xffff0000, v132
	v_lshlrev_b32_e32 v22, 16, v134
	v_and_b32_e32 v23, 0xffff0000, v134
	v_lshlrev_b32_e32 v24, 16, v135
	v_and_b32_e32 v25, 0xffff0000, v135
	v_mov_b32_e32 v26, v39
	v_pk_fma_f32 v[14:15], v[18:19], v[26:27], v[14:15] op_sel_hi:[1,0,1]
	v_pk_fma_f32 v[12:13], v[16:17], v[26:27], v[12:13] op_sel_hi:[1,0,1]
	v_pk_fma_f32 v[10:11], v[10:11], v[26:27], v[24:25] op_sel_hi:[1,0,1]
	v_pk_fma_f32 v[8:9], v[8:9], v[26:27], v[22:23] op_sel_hi:[1,0,1]
	global_store_dwordx4 v[20:21], v[12:15], off
	global_store_dwordx4 v[20:21], v[8:11], off offset:16
	s_nop 0
	v_lshlrev_b32_e32 v12, 16, v130
	v_lshlrev_b32_e32 v8, 16, v128
	v_and_b32_e32 v9, 0xffff0000, v128
	v_lshlrev_b32_e32 v10, 16, v129
	v_and_b32_e32 v11, 0xffff0000, v129
	v_and_b32_e32 v13, 0xffff0000, v130
	v_lshlrev_b32_e32 v14, 16, v131
	v_and_b32_e32 v15, 0xffff0000, v131
	v_pk_fma_f32 v[6:7], v[6:7], v[26:27], v[10:11] op_sel_hi:[1,0,1]
	v_pk_fma_f32 v[4:5], v[4:5], v[26:27], v[8:9] op_sel_hi:[1,0,1]
	v_pk_fma_f32 v[2:3], v[2:3], v[26:27], v[14:15] op_sel_hi:[1,0,1]
	v_pk_fma_f32 v[0:1], v[0:1], v[26:27], v[12:13] op_sel_hi:[1,0,1]
	global_store_dwordx4 v[20:21], v[4:7], off offset:512
	global_store_dwordx4 v[20:21], v[0:3], off offset:528
	s_cbranch_vccz .LBB0_517
	s_waitcnt vmcnt(0)
	s_cmpk_gt_u32 s33, 0xff
	s_cbranch_scc1 .LBB0_526
	s_barrier
